# P3 conv-tap loads batched one head ahead; scan loop: u prefetch in flight whole step, o-store block via cvt_pk+dpp+perm in MFMA gaps
# speedup vs baseline: 1.0245x; 1.0245x over previous
.LBB0_185:
	s_ashr_i32 s8, s4, 5
	s_and_b32 s29, s4, 31
	s_ashr_i32 s9, s8, 31
	s_lshl_b32 s28, s29, 6
	s_lshl_b64 s[12:13], s[8:9], 11
	v_ashrrev_i32_e32 v244, 3, v35
	s_add_i32 s98, s12, s28
	v_add_u32_e32 v244, s98, v244
	v_and_b32_e32 v246, 7, v35
	v_lshlrev_b32_e32 v246, 5, v246
	v_mov_b32_e32 v247, 0
	v_lshl_add_u64 v[246:247], s[62:63], 0, v[246:247]
	v_mad_u64_u32 v[240:241], s[98:99], v244, s91, v[246:247]
	v_mov_b32_e32 v244, 0xffffe800
	v_add_co_u32_e64 v242, s[98:99], v240, v244
	s_nop 1
	v_addc_co_u32_e64 v243, s[98:99], v241, -1, s[98:99]
	global_load_dwordx4 v[192:195], v[240:241], off
	global_load_dwordx4 v[212:215], v[240:241], off offset:16
	global_load_dwordx4 v[168:171], v[240:241], off offset:-3072
	global_load_dwordx4 v[172:175], v[240:241], off offset:-3056
	global_load_dwordx4 v[140:143], v[242:243], off
	global_load_dwordx4 v[144:147], v[242:243], off offset:16
	global_load_dwordx4 v[116:119], v[242:243], off offset:-3072
	global_load_dwordx4 v[120:123], v[242:243], off offset:-3056
	global_load_dwordx4 v[216:219], v[240:241], off offset:1024
	global_load_dwordx4 v[220:223], v[240:241], off offset:1040
	global_load_dwordx4 v[176:179], v[240:241], off offset:-2048
	global_load_dwordx4 v[180:183], v[240:241], off offset:-2032
	global_load_dwordx4 v[148:151], v[242:243], off offset:1024
	global_load_dwordx4 v[152:155], v[242:243], off offset:1040
	global_load_dwordx4 v[124:127], v[242:243], off offset:-2048
	global_load_dwordx4 v[128:131], v[242:243], off offset:-2032
	global_load_dwordx4 v[232:235], v[240:241], off offset:2048
	global_load_dwordx4 v[236:239], v[240:241], off offset:2064
	global_load_dwordx4 v[184:187], v[240:241], off offset:-1024
	global_load_dwordx4 v[188:191], v[240:241], off offset:-1008
	global_load_dwordx4 v[156:159], v[242:243], off offset:2048
	global_load_dwordx4 v[164:167], v[242:243], off offset:2064
	global_load_dwordx4 v[132:135], v[242:243], off offset:-1024
	global_load_dwordx4 v[136:139], v[242:243], off offset:-1008
	s_and_saveexec_b64 s[52:53], s[38:39]
	s_cbranch_execz .LBB0_187
	s_add_u32 s30, s12, s28
	s_addc_u32 s31, s13, 0
	v_lshl_add_u64 v[0:1], s[30:31], 0, v[32:33]
	v_lshlrev_b64 v[0:1], 4, v[0:1]
	v_lshl_or_b32 v0, v34, 2, v0
	v_lshl_add_u64 v[2:3], s[16:17], 0, v[0:1]
	v_lshl_add_u64 v[0:1], s[18:19], 0, v[0:1]
	global_load_dword v2, v[2:3], off
	s_nop 0
	global_load_dword v0, v[0:1], off
	s_waitcnt vmcnt(1)
	ds_write_b32 v38, v2
	s_waitcnt vmcnt(0)
	ds_write_b32 v39, v0

.LBB0_199:
	s_or_b64 exec, exec, s[8:9]
	v_ashrrev_i32_e32 v29, 3, v36
	s_lshl_b32 s74, s31, 6
	v_add_lshl_u32 v0, v29, s74, 2
	s_lshl_b32 s34, s31, 8
	s_waitcnt lgkmcnt(0)
	s_barrier
	s_waitcnt vmcnt(0)
	v_add_u32_e32 v1, s84, v0
	v_add_u32_e32 v0, 0, v0
	s_add_i32 s35, s84, s34
	v_add_u32_e32 v0, 0x1cc00, v0
	v_mov_b32_e32 v3, s35
	ds_read_b32 v31, v1
	ds_read_b32 v26, v0
	ds_read_b32 v37, v3 offset:252
	v_and_b32_e32 v27, 7, v36
	v_lshlrev_b32_e32 v30, 4, v27
	v_or_b32_e32 v2, s56, v30
	v_add_u32_e32 v6, s30, v29
	v_lshlrev_b32_e32 v196, 1, v2
	v_mov_b32_e32 v2, 0
	v_lshl_add_u32 v28, v27, 6, s86
	v_lshl_add_u64 v[0:1], s[62:63], 0, v[196:197]
	v_cmp_lt_i32_e64 s[56:57], -1, v6
	v_mov_b32_e32 v3, 0
	v_mov_b32_e32 v14, 0
	v_mov_b32_e32 v15, 0
	v_mov_b32_e32 v20, 0
	v_mov_b32_e32 v21, v2
	v_mov_b32_e32 v16, v2
	v_mov_b32_e32 v17, v2
	v_mov_b32_e32 v18, v2
	v_mov_b32_e32 v19, v2
	v_mov_b32_e32 v8, v2
	v_mov_b32_e32 v9, v2
	v_mov_b32_e32 v10, v2
	v_mov_b32_e32 v11, v2
	v_mov_b32_e32 v12, v2
	v_mov_b32_e32 v13, v2
	v_mov_b32_e32 v22, 0
	v_mov_b32_e32 v23, 0
	s_and_saveexec_b64 s[8:9], s[56:57]
	s_cbranch_execz .LBB0_201
	v_mov_b32_e32 v7, v197
	v_lshl_add_u64 v[2:3], s[12:13], 0, v[6:7]
	v_mad_u64_u32 v[8:9], s[52:53], v2, s91, v[0:1]
	v_mad_i32_i24 v9, v3, s91, v9
	ds_read_b128 v[14:17], v28
	ds_read_b128 v[22:25], v28 offset:16
	ds_read_b128 v[42:45], v28 offset:32
	ds_read_b128 v[46:49], v28 offset:48
	v_lshlrev_b32_e32 v12, 16, v116
	v_and_b32_e32 v13, 0xffff0000, v116
	v_lshlrev_b32_e32 v8, 16, v117
	v_and_b32_e32 v9, 0xffff0000, v117
	s_waitcnt lgkmcnt(3)
	v_pk_fma_f32 v[20:21], v[16:17], v[8:9], 0 op_sel_hi:[1,1,0]
	v_lshlrev_b32_e32 v8, 16, v118
	v_and_b32_e32 v9, 0xffff0000, v118
	s_waitcnt lgkmcnt(2)
	v_pk_fma_f32 v[16:17], v[22:23], v[8:9], 0 op_sel_hi:[1,1,0]
	v_lshlrev_b32_e32 v8, 16, v119
	v_and_b32_e32 v9, 0xffff0000, v119
	v_pk_fma_f32 v[18:19], v[24:25], v[8:9], 0 op_sel_hi:[1,1,0]
	v_lshlrev_b32_e32 v8, 16, v120
	v_and_b32_e32 v9, 0xffff0000, v120
	v_lshlrev_b32_e32 v2, 16, v121
	v_and_b32_e32 v3, 0xffff0000, v121
	s_waitcnt lgkmcnt(1)
	v_pk_fma_f32 v[10:11], v[44:45], v[2:3], 0 op_sel_hi:[1,1,0]
	v_lshlrev_b32_e32 v2, 16, v122
	v_and_b32_e32 v3, 0xffff0000, v122
	v_pk_fma_f32 v[14:15], v[14:15], v[12:13], 0 op_sel_hi:[1,1,0]
	s_waitcnt lgkmcnt(0)
	v_pk_fma_f32 v[12:13], v[46:47], v[2:3], 0 op_sel_hi:[1,1,0]
	v_lshlrev_b32_e32 v2, 16, v123
	v_and_b32_e32 v3, 0xffff0000, v123
	v_pk_fma_f32 v[2:3], v[48:49], v[2:3], 0 op_sel_hi:[1,1,0]
	v_pk_fma_f32 v[8:9], v[42:43], v[8:9], 0 op_sel_hi:[1,1,0]
	v_mov_b32_e32 v22, v2
	v_mov_b32_e32 v23, v3
.LBB0_201:
	s_or_b64 exec, exec, s[8:9]
	v_add_u32_e32 v196, 1, v6
	v_cmp_lt_i32_e64 s[58:59], -2, v6
	s_and_saveexec_b64 s[8:9], s[58:59]
	s_cbranch_execz .LBB0_203
	v_lshl_add_u64 v[4:5], s[12:13], 0, v[196:197]
	v_mad_u64_u32 v[42:43], s[52:53], v4, s91, v[0:1]
	v_mad_i32_i24 v43, v5, s91, v43
	ds_read_b128 v[46:49], v28 offset:512
	ds_read_b128 v[50:53], v28 offset:528
	ds_read_b128 v[54:57], v28 offset:544
	ds_read_b128 v[58:61], v28 offset:560
	v_lshlrev_b32_e32 v4, 16, v140
	v_and_b32_e32 v5, 0xffff0000, v140
	s_waitcnt lgkmcnt(3)
	v_pk_fma_f32 v[14:15], v[46:47], v[4:5], v[14:15]
	v_lshlrev_b32_e32 v4, 16, v141
	v_and_b32_e32 v5, 0xffff0000, v141
	v_pk_fma_f32 v[20:21], v[48:49], v[4:5], v[20:21]
	v_lshlrev_b32_e32 v4, 16, v142
	v_and_b32_e32 v5, 0xffff0000, v142
	s_waitcnt lgkmcnt(2)
	v_pk_fma_f32 v[16:17], v[50:51], v[4:5], v[16:17]
	v_lshlrev_b32_e32 v4, 16, v143
	v_and_b32_e32 v5, 0xffff0000, v143
	v_pk_fma_f32 v[18:19], v[52:53], v[4:5], v[18:19]
	v_lshlrev_b32_e32 v4, 16, v144
	v_and_b32_e32 v5, 0xffff0000, v144
	s_waitcnt lgkmcnt(1)
	v_pk_fma_f32 v[8:9], v[54:55], v[4:5], v[8:9]
	v_lshlrev_b32_e32 v4, 16, v145
	v_and_b32_e32 v5, 0xffff0000, v145
	v_pk_fma_f32 v[10:11], v[56:57], v[4:5], v[10:11]
	v_lshlrev_b32_e32 v4, 16, v146
	v_and_b32_e32 v5, 0xffff0000, v146
	s_waitcnt lgkmcnt(0)
	v_pk_fma_f32 v[12:13], v[58:59], v[4:5], v[12:13]
	v_lshlrev_b32_e32 v4, 16, v147
	v_and_b32_e32 v5, 0xffff0000, v147
	v_pk_fma_f32 v[22:23], v[60:61], v[4:5], v[2:3]
.LBB0_203:
	s_or_b64 exec, exec, s[8:9]
	v_add_u32_e32 v4, 2, v6
	v_cmp_lt_i32_e64 s[54:55], -3, v6
	s_and_saveexec_b64 s[8:9], s[54:55]
	s_cbranch_execz .LBB0_205
	v_mov_b32_e32 v5, v197
	v_lshl_add_u64 v[2:3], s[12:13], 0, v[4:5]
	v_mad_u64_u32 v[24:25], s[52:53], v2, s91, v[0:1]
	v_mad_i32_i24 v25, v3, s91, v25
	ds_read_b128 v[50:53], v28 offset:1024
	ds_read_b128 v[54:57], v28 offset:1040
	ds_read_b128 v[58:61], v28 offset:1056
	ds_read_b128 v[62:65], v28 offset:1072
	v_lshlrev_b32_e32 v2, 16, v168
	v_and_b32_e32 v3, 0xffff0000, v168
	s_waitcnt lgkmcnt(3)
	v_pk_fma_f32 v[14:15], v[50:51], v[2:3], v[14:15]
	v_lshlrev_b32_e32 v2, 16, v169
	v_and_b32_e32 v3, 0xffff0000, v169
	v_pk_fma_f32 v[20:21], v[52:53], v[2:3], v[20:21]
	v_lshlrev_b32_e32 v2, 16, v170
	v_and_b32_e32 v3, 0xffff0000, v170
	s_waitcnt lgkmcnt(2)
	v_pk_fma_f32 v[16:17], v[54:55], v[2:3], v[16:17]
	v_lshlrev_b32_e32 v2, 16, v171
	v_and_b32_e32 v3, 0xffff0000, v171
	v_pk_fma_f32 v[18:19], v[56:57], v[2:3], v[18:19]
	v_lshlrev_b32_e32 v2, 16, v172
	v_and_b32_e32 v3, 0xffff0000, v172
	s_waitcnt lgkmcnt(1)
	v_pk_fma_f32 v[8:9], v[58:59], v[2:3], v[8:9]
	v_lshlrev_b32_e32 v2, 16, v173
	v_and_b32_e32 v3, 0xffff0000, v173
	v_pk_fma_f32 v[10:11], v[60:61], v[2:3], v[10:11]
	v_lshlrev_b32_e32 v2, 16, v174
	v_and_b32_e32 v3, 0xffff0000, v174
	s_waitcnt lgkmcnt(0)
	v_pk_fma_f32 v[12:13], v[62:63], v[2:3], v[12:13]
	v_lshlrev_b32_e32 v2, 16, v175
	v_and_b32_e32 v3, 0xffff0000, v175
	v_pk_fma_f32 v[22:23], v[64:65], v[2:3], v[22:23]
.LBB0_205:
	s_or_b64 exec, exec, s[8:9]
	v_add_u32_e32 v2, s28, v29
	v_cmp_lt_i32_e64 s[52:53], -1, v2
	s_and_saveexec_b64 s[8:9], s[52:53]
	s_cbranch_execz .LBB0_207
	v_mov_b32_e32 v3, v197
	v_lshl_add_u64 v[24:25], s[12:13], 0, v[2:3]
	v_mad_u64_u32 v[46:47], s[76:77], v24, s91, v[0:1]
	v_mad_i32_i24 v47, v25, s91, v47
	ds_read_b128 v[50:53], v28 offset:1536
	ds_read_b128 v[54:57], v28 offset:1552
	ds_read_b128 v[58:61], v28 offset:1568
	ds_read_b128 v[62:65], v28 offset:1584
	v_lshlrev_b32_e32 v24, 16, v192
	v_and_b32_e32 v25, 0xffff0000, v192
	s_waitcnt lgkmcnt(3)
	v_pk_fma_f32 v[14:15], v[50:51], v[24:25], v[14:15]
	v_lshlrev_b32_e32 v24, 16, v193
	v_and_b32_e32 v25, 0xffff0000, v193
	v_pk_fma_f32 v[20:21], v[52:53], v[24:25], v[20:21]
	v_lshlrev_b32_e32 v24, 16, v194
	v_and_b32_e32 v25, 0xffff0000, v194
	s_waitcnt lgkmcnt(2)
	v_pk_fma_f32 v[16:17], v[54:55], v[24:25], v[16:17]
	v_lshlrev_b32_e32 v24, 16, v195
	v_and_b32_e32 v25, 0xffff0000, v195
	v_pk_fma_f32 v[18:19], v[56:57], v[24:25], v[18:19]
	v_lshlrev_b32_e32 v24, 16, v212
	v_and_b32_e32 v25, 0xffff0000, v212
	s_waitcnt lgkmcnt(1)
	v_pk_fma_f32 v[8:9], v[58:59], v[24:25], v[8:9]
	v_lshlrev_b32_e32 v24, 16, v213
	v_and_b32_e32 v25, 0xffff0000, v213
	v_pk_fma_f32 v[10:11], v[60:61], v[24:25], v[10:11]
	v_lshlrev_b32_e32 v24, 16, v214
	v_and_b32_e32 v25, 0xffff0000, v214
	s_waitcnt lgkmcnt(0)
	v_pk_fma_f32 v[12:13], v[62:63], v[24:25], v[12:13]
	v_lshlrev_b32_e32 v24, 16, v215
	v_and_b32_e32 v25, 0xffff0000, v215
	v_pk_fma_f32 v[22:23], v[64:65], v[24:25], v[22:23]

.LBB0_211:
	v_mov_b32_e32 v3, v197
	v_lshl_add_u64 v[24:25], s[12:13], 0, v[2:3]
	v_mad_u64_u32 v[52:53], vcc, v24, s91, v[0:1]
	v_mad_i32_i24 v53, v25, s91, v53
	ds_read_b128 v[56:59], v28 offset:3584
	ds_read_b128 v[60:63], v28 offset:3600
	ds_read_b128 v[64:67], v28 offset:3616
	ds_read_b128 v[68:71], v28 offset:3632
	v_lshlrev_b32_e32 v24, 16, v216
	v_and_b32_e32 v25, 0xffff0000, v216
	s_waitcnt lgkmcnt(3)
	v_pk_fma_f32 v[22:23], v[56:57], v[24:25], v[22:23]
	v_lshlrev_b32_e32 v24, 16, v217
	v_and_b32_e32 v25, 0xffff0000, v217
	v_pk_fma_f32 v[18:19], v[58:59], v[24:25], v[18:19]
	v_lshlrev_b32_e32 v24, 16, v218
	v_and_b32_e32 v25, 0xffff0000, v218
	s_waitcnt lgkmcnt(2)
	v_pk_fma_f32 v[16:17], v[60:61], v[24:25], v[16:17]
	v_lshlrev_b32_e32 v24, 16, v219
	v_and_b32_e32 v25, 0xffff0000, v219
	v_pk_fma_f32 v[14:15], v[62:63], v[24:25], v[14:15]
	v_lshlrev_b32_e32 v24, 16, v220
	v_and_b32_e32 v25, 0xffff0000, v220
	s_waitcnt lgkmcnt(1)
	v_pk_fma_f32 v[8:9], v[64:65], v[24:25], v[8:9]
	v_lshlrev_b32_e32 v24, 16, v221
	v_and_b32_e32 v25, 0xffff0000, v221
	v_pk_fma_f32 v[10:11], v[66:67], v[24:25], v[10:11]
	v_lshlrev_b32_e32 v24, 16, v222
	v_and_b32_e32 v25, 0xffff0000, v222
	s_waitcnt lgkmcnt(0)
	v_pk_fma_f32 v[12:13], v[68:69], v[24:25], v[12:13]
	v_lshlrev_b32_e32 v24, 16, v223
	v_and_b32_e32 v25, 0xffff0000, v223
	v_pk_fma_f32 v[20:21], v[70:71], v[24:25], v[20:21]

.LBB0_216:
	v_mov_b32_e32 v3, v197
	v_lshl_add_u64 v[2:3], s[12:13], 0, v[2:3]
	v_mad_u64_u32 v[4:5], s[52:53], v2, s91, v[0:1]
	v_mad_i32_i24 v5, v3, s91, v5
	ds_read_b128 v[42:45], v28 offset:5632
	ds_read_b128 v[46:49], v28 offset:5648
	ds_read_b128 v[50:53], v28 offset:5664
	ds_read_b128 v[54:57], v28 offset:5680
	v_lshlrev_b32_e32 v24, 16, v232
	v_and_b32_e32 v25, 0xffff0000, v232
	v_lshlrev_b32_e32 v4, 16, v233
	v_and_b32_e32 v5, 0xffff0000, v233
	s_waitcnt lgkmcnt(3)
	v_pk_fma_f32 v[18:19], v[44:45], v[4:5], v[18:19]
	v_lshlrev_b32_e32 v4, 16, v234
	v_and_b32_e32 v5, 0xffff0000, v234
	s_waitcnt lgkmcnt(2)
	v_pk_fma_f32 v[16:17], v[46:47], v[4:5], v[16:17]
	v_lshlrev_b32_e32 v4, 16, v235
	v_and_b32_e32 v5, 0xffff0000, v235
	v_pk_fma_f32 v[14:15], v[48:49], v[4:5], v[14:15]
	v_lshlrev_b32_e32 v4, 16, v236
	v_and_b32_e32 v5, 0xffff0000, v236
	v_lshlrev_b32_e32 v0, 16, v237
	v_and_b32_e32 v1, 0xffff0000, v237
	s_waitcnt lgkmcnt(1)
	v_pk_fma_f32 v[10:11], v[52:53], v[0:1], v[10:11]
	v_lshlrev_b32_e32 v0, 16, v238
	v_and_b32_e32 v1, 0xffff0000, v238
	s_waitcnt lgkmcnt(0)
	v_pk_fma_f32 v[8:9], v[54:55], v[0:1], v[8:9]
	v_lshlrev_b32_e32 v0, 16, v239
	v_and_b32_e32 v1, 0xffff0000, v239
	v_pk_fma_f32 v[20:21], v[42:43], v[24:25], v[20:21]
	v_pk_fma_f32 v[12:13], v[50:51], v[4:5], v[12:13]
	v_pk_fma_f32 v[22:23], v[56:57], v[0:1], v[22:23]
.LBB0_217:
	s_or_b64 exec, exec, s[54:55]
	v_mul_f32_e32 v7, 0xbfb8aa3b, v14
	v_exp_f32_e32 v7, v7
	v_mul_f32_e32 v1, 0xbfb8aa3b, v20
	v_exp_f32_e32 v1, v1
	v_mul_f32_e32 v5, 0xbfb8aa3b, v16
	v_add_f32_e32 v7, 1.0, v7
	v_rcp_f32_e32 v7, v7
	v_exp_f32_e32 v5, v5
	v_mul_f32_e32 v2, 0xbfb8aa3b, v21
	v_add_f32_e32 v1, 1.0, v1
	v_mul_f32_e32 v7, v14, v7
	v_mul_f32_e32 v14, 0xbfb8aa3b, v15
	v_exp_f32_e32 v14, v14
	v_exp_f32_e32 v2, v2
	v_rcp_f32_e32 v1, v1
	v_mul_f32_e32 v3, 0xbfb8aa3b, v18
	v_add_f32_e32 v14, 1.0, v14
	v_rcp_f32_e32 v14, v14
	v_add_f32_e32 v5, 1.0, v5
	v_exp_f32_e32 v3, v3
	v_rcp_f32_e32 v5, v5
	v_mul_f32_e32 v14, v15, v14
	v_mul_f32_e32 v15, 0xbfb8aa3b, v12
	v_exp_f32_e32 v15, v15
	v_add_f32_e32 v2, 1.0, v2
	v_mul_f32_e32 v1, v20, v1
	v_rcp_f32_e32 v2, v2
	v_add_f32_e32 v15, 1.0, v15
	v_rcp_f32_e32 v15, v15
	v_mul_f32_e32 v4, 0xbfb8aa3b, v19
	v_exp_f32_e32 v4, v4
	v_mul_f32_e32 v1, v26, v1
	v_mul_f32_e32 v12, v12, v15
	v_mul_f32_e32 v15, 0xbfb8aa3b, v13
	v_exp_f32_e32 v15, v15
	v_add_f32_e32 v3, 1.0, v3
	v_mul_f32_e32 v5, v16, v5
	v_bfe_u32 v16, v1, 16, 1
	v_add_f32_e32 v15, 1.0, v15
	v_rcp_f32_e32 v15, v15
	v_rcp_f32_e32 v3, v3
	v_add3_u32 v1, v1, v16, s83
	v_mul_u32_u24_e32 v16, 0x900, v27
	v_mul_f32_e32 v13, v13, v15
	v_mul_f32_e32 v15, 0xbfb8aa3b, v10
	v_exp_f32_e32 v15, v15
	v_mul_f32_e32 v2, v21, v2
	v_add3_u32 v16, 0, v29, v16
	v_add_f32_e32 v4, 1.0, v4
	v_add_f32_e32 v15, 1.0, v15
	v_rcp_f32_e32 v15, v15
	ds_write_b16_d16_hi v16, v1 offset:53248
	v_mul_f32_e32 v1, v26, v2
	v_rcp_f32_e32 v4, v4
	v_mul_f32_e32 v10, v10, v15
	v_mul_f32_e32 v15, 0xbfb8aa3b, v11
	v_exp_f32_e32 v15, v15
	v_mul_f32_e32 v6, 0xbfb8aa3b, v17
	v_bfe_u32 v2, v1, 16, 1
	v_mul_f32_e32 v3, v18, v3
	v_exp_f32_e32 v6, v6
	v_add3_u32 v1, v1, v2, s83
	v_add_f32_e32 v15, 1.0, v15
	ds_write_b16_d16_hi v16, v1 offset:53392
	v_mul_f32_e32 v1, v26, v3
	v_rcp_f32_e32 v15, v15
	v_bfe_u32 v2, v1, 16, 1
	v_mul_f32_e32 v4, v19, v4
	v_add3_u32 v1, v1, v2, s83
	v_add_f32_e32 v6, 1.0, v6
	ds_write_b16_d16_hi v16, v1 offset:53536
	v_mul_f32_e32 v1, v26, v4
	v_rcp_f32_e32 v6, v6
	v_bfe_u32 v2, v1, 16, 1
	v_mul_f32_e32 v11, v11, v15
	v_mul_f32_e32 v15, 0xbfb8aa3b, v8
	v_add3_u32 v1, v1, v2, s83
	v_exp_f32_e32 v15, v15
	ds_write_b16_d16_hi v16, v1 offset:53680
	v_mul_f32_e32 v1, v26, v5
	v_bfe_u32 v2, v1, 16, 1
	v_mul_f32_e32 v6, v17, v6
	v_add3_u32 v1, v1, v2, s83
	ds_write_b16_d16_hi v16, v1 offset:53824
	v_mul_f32_e32 v1, v26, v6
	v_add_f32_e32 v15, 1.0, v15
	v_bfe_u32 v2, v1, 16, 1
	v_rcp_f32_e32 v15, v15
	v_add3_u32 v1, v1, v2, s83
	ds_write_b16_d16_hi v16, v1 offset:53968
	v_mul_f32_e32 v1, v26, v7
	v_bfe_u32 v2, v1, 16, 1
	v_add3_u32 v1, v1, v2, s83
	v_mul_f32_e32 v8, v8, v15
	v_mul_f32_e32 v15, 0xbfb8aa3b, v9
	ds_write_b16_d16_hi v16, v1 offset:54112
	v_mul_f32_e32 v1, v26, v14
	v_exp_f32_e32 v15, v15
	v_bfe_u32 v2, v1, 16, 1
	v_add3_u32 v1, v1, v2, s83
	ds_write_b16_d16_hi v16, v1 offset:54256
	v_mul_f32_e32 v1, v26, v12
	v_bfe_u32 v2, v1, 16, 1
	v_add_f32_e32 v15, 1.0, v15
	v_add3_u32 v1, v1, v2, s83
	v_rcp_f32_e32 v15, v15
	ds_write_b16_d16_hi v16, v1 offset:54400
	v_mul_f32_e32 v1, v26, v13
	v_bfe_u32 v2, v1, 16, 1
	v_add3_u32 v1, v1, v2, s83
	ds_write_b16_d16_hi v16, v1 offset:54544
	v_mul_f32_e32 v1, v26, v10
	v_mul_f32_e32 v9, v9, v15
	v_mul_f32_e32 v15, 0xbfb8aa3b, v22
	v_bfe_u32 v2, v1, 16, 1
	v_exp_f32_e32 v15, v15
	v_add3_u32 v1, v1, v2, s83
	v_mul_f32_e32 v0, 0xbfb8aa3b, v23
	ds_write_b16_d16_hi v16, v1 offset:54688
	v_mul_f32_e32 v1, v26, v11
	v_exp_f32_e32 v0, v0
	v_bfe_u32 v2, v1, 16, 1
	v_add3_u32 v1, v1, v2, s83
	v_add_f32_e32 v15, 1.0, v15
	ds_write_b16_d16_hi v16, v1 offset:54832
	v_mul_f32_e32 v1, v26, v8
	v_rcp_f32_e32 v15, v15
	v_bfe_u32 v2, v1, 16, 1
	v_add_f32_e32 v0, 1.0, v0
	v_add3_u32 v1, v1, v2, s83
	v_rcp_f32_e32 v0, v0
	ds_write_b16_d16_hi v16, v1 offset:54976
	v_mul_f32_e32 v1, v26, v9
	v_bfe_u32 v2, v1, 16, 1
	v_mul_f32_e32 v15, v22, v15
	v_add3_u32 v1, v1, v2, s83
	ds_write_b16_d16_hi v16, v1 offset:55120
	v_mul_f32_e32 v1, v26, v15
	v_mul_f32_e32 v0, v23, v0
	v_bfe_u32 v2, v1, 16, 1
	v_add3_u32 v1, v1, v2, s83
	v_mul_f32_e32 v0, v26, v0
	ds_write_b16_d16_hi v16, v1 offset:55264
	v_bfe_u32 v1, v0, 16, 1
	v_add3_u32 v0, v0, v1, s83
	ds_write_b16_d16_hi v16, v0 offset:55408
	v_and_b32_e32 v42, 31, v36
	s_cmp_lt_u32 s31, 3
	s_cbranch_scc0 .Lp3_pf_skip
	v_ashrrev_i32_e32 v244, 3, v35
	s_add_i32 s98, s12, s28
	v_add_u32_e32 v244, s98, v244
	v_and_b32_e32 v246, 7, v35
	v_lshlrev_b32_e32 v246, 5, v246
	s_lshl_b32 s98, s31, 8
	s_addk_i32 s98, 0x100
	v_or_b32_e32 v246, s98, v246
	v_mov_b32_e32 v247, 0
	v_lshl_add_u64 v[246:247], s[62:63], 0, v[246:247]
	v_mad_u64_u32 v[240:241], s[98:99], v244, s91, v[246:247]
	v_mov_b32_e32 v244, 0xffffe800
	v_add_co_u32_e64 v242, s[98:99], v240, v244
	s_nop 1
	v_addc_co_u32_e64 v243, s[98:99], v241, -1, s[98:99]
	global_load_dwordx4 v[192:195], v[240:241], off
	global_load_dwordx4 v[212:215], v[240:241], off offset:16
	global_load_dwordx4 v[168:171], v[240:241], off offset:-3072
	global_load_dwordx4 v[172:175], v[240:241], off offset:-3056
	global_load_dwordx4 v[140:143], v[242:243], off
	global_load_dwordx4 v[144:147], v[242:243], off offset:16
	global_load_dwordx4 v[116:119], v[242:243], off offset:-3072
	global_load_dwordx4 v[120:123], v[242:243], off offset:-3056
	global_load_dwordx4 v[216:219], v[240:241], off offset:1024
	global_load_dwordx4 v[220:223], v[240:241], off offset:1040
	global_load_dwordx4 v[176:179], v[240:241], off offset:-2048
	global_load_dwordx4 v[180:183], v[240:241], off offset:-2032
	global_load_dwordx4 v[148:151], v[242:243], off offset:1024
	global_load_dwordx4 v[152:155], v[242:243], off offset:1040
	global_load_dwordx4 v[124:127], v[242:243], off offset:-2048
	global_load_dwordx4 v[128:131], v[242:243], off offset:-2032
	global_load_dwordx4 v[232:235], v[240:241], off offset:2048
	global_load_dwordx4 v[236:239], v[240:241], off offset:2064
	global_load_dwordx4 v[184:187], v[240:241], off offset:-1024
	global_load_dwordx4 v[188:191], v[240:241], off offset:-1008
	global_load_dwordx4 v[156:159], v[242:243], off offset:2048
	global_load_dwordx4 v[164:167], v[242:243], off offset:2064
	global_load_dwordx4 v[132:135], v[242:243], off offset:-1024
	global_load_dwordx4 v[136:139], v[242:243], off offset:-1008
.Lp3_pf_skip:
	s_waitcnt lgkmcnt(0)
	s_barrier
	v_bfe_u32 v37, v36, 5, 1
	v_or_b32_e32 v25, s36, v42
	v_lshlrev_b32_e32 v24, 3, v37
	v_mul_u32_u24_e32 v31, 0x110, v25
	v_mov_b32_e32 v0, 0
	s_andn2_b64 vcc, exec, s[64:65]
	v_mov_b32_e32 v1, 0
	v_mov_b32_e32 v2, 0
	v_mov_b32_e32 v3, 0
	v_mov_b32_e32 v4, 0
	v_mov_b32_e32 v5, 0
	v_mov_b32_e32 v6, 0
	v_mov_b32_e32 v7, 0
	v_mov_b32_e32 v8, 0
	v_mov_b32_e32 v9, 0
	v_mov_b32_e32 v10, 0
	v_mov_b32_e32 v11, 0
	v_mov_b32_e32 v12, 0
	v_mov_b32_e32 v13, 0
	v_mov_b32_e32 v14, 0
	v_mov_b32_e32 v15, 0
	s_cbranch_vccnz .LBB0_219
	v_or_b32_e32 v0, s2, v42
	v_lshlrev_b32_e32 v4, 1, v24
	v_mul_u32_u24_e32 v0, 0x110, v0
	v_add3_u32 v26, s23, v0, v4
	ds_read_b128 v[0:3], v26
	v_add3_u32 v27, 0, v31, v4
	ds_read_b128 v[4:7], v27
	ds_read_b128 v[16:19], v26 offset:32
	ds_read_b128 v[20:23], v27 offset:32
	s_waitcnt lgkmcnt(2)
	v_mfma_f32_32x32x16_bf16 v[0:15], v[0:3], v[4:7], 0
	s_waitcnt lgkmcnt(0)
	v_mfma_f32_32x32x16_bf16 v[0:15], v[16:19], v[20:23], v[0:15]
	ds_read_b128 v[16:19], v26 offset:64
	ds_read_b128 v[20:23], v27 offset:64
	s_waitcnt lgkmcnt(0)
	v_mfma_f32_32x32x16_bf16 v[0:15], v[16:19], v[20:23], v[0:15]
	ds_read_b128 v[16:19], v26 offset:96
	ds_read_b128 v[20:23], v27 offset:96
	s_waitcnt lgkmcnt(0)
	v_mfma_f32_32x32x16_bf16 v[0:15], v[16:19], v[20:23], v[0:15]
	ds_read_b128 v[16:19], v26 offset:128
	ds_read_b128 v[20:23], v27 offset:128
	s_waitcnt lgkmcnt(0)
	v_mfma_f32_32x32x16_bf16 v[0:15], v[16:19], v[20:23], v[0:15]
	ds_read_b128 v[16:19], v26 offset:160
	ds_read_b128 v[20:23], v27 offset:160
	s_waitcnt lgkmcnt(0)
	v_mfma_f32_32x32x16_bf16 v[0:15], v[16:19], v[20:23], v[0:15]
	ds_read_b128 v[16:19], v26 offset:192
	ds_read_b128 v[20:23], v27 offset:192
	s_waitcnt lgkmcnt(0)
	v_mfma_f32_32x32x16_bf16 v[0:15], v[16:19], v[20:23], v[0:15]
	ds_read_b128 v[16:19], v26 offset:224
	ds_read_b128 v[20:23], v27 offset:224
	s_waitcnt lgkmcnt(0)
	v_mfma_f32_32x32x16_bf16 v[0:15], v[16:19], v[20:23], v[0:15]

.LBB0_302:
	v_mov_b32_e32 v7, v197
	v_lshl_add_u64 v[8:9], s[12:13], 0, v[6:7]
	v_mad_u64_u32 v[10:11], vcc, v8, s91, v[0:1]
	v_mad_i32_i24 v11, v9, s91, v11
	ds_read_b128 v[12:15], v28 offset:2048
	ds_read_b128 v[52:55], v28 offset:2064
	ds_read_b128 v[56:59], v28 offset:2080
	ds_read_b128 v[60:63], v28 offset:2096
	v_lshlrev_b32_e32 v20, 16, v131
	v_lshlrev_b32_e32 v16, 16, v124
	v_and_b32_e32 v17, 0xffff0000, v124
	v_lshlrev_b32_e32 v8, 16, v125
	v_and_b32_e32 v9, 0xffff0000, v125
	s_waitcnt lgkmcnt(3)
	v_pk_fma_f32 v[18:19], v[14:15], v[8:9], 0 op_sel_hi:[1,1,0]
	v_lshlrev_b32_e32 v8, 16, v126
	v_and_b32_e32 v9, 0xffff0000, v126
	v_pk_fma_f32 v[22:23], v[12:13], v[16:17], 0 op_sel_hi:[1,1,0]
	s_waitcnt lgkmcnt(2)
	v_pk_fma_f32 v[16:17], v[52:53], v[8:9], 0 op_sel_hi:[1,1,0]
	v_lshlrev_b32_e32 v8, 16, v127
	v_and_b32_e32 v9, 0xffff0000, v127
	v_and_b32_e32 v21, 0xffff0000, v131
	v_pk_fma_f32 v[14:15], v[54:55], v[8:9], 0 op_sel_hi:[1,1,0]
	v_lshlrev_b32_e32 v8, 16, v128
	v_and_b32_e32 v9, 0xffff0000, v128
	v_lshlrev_b32_e32 v10, 16, v129
	v_and_b32_e32 v11, 0xffff0000, v129
	v_lshlrev_b32_e32 v12, 16, v130
	v_and_b32_e32 v13, 0xffff0000, v130
	s_waitcnt lgkmcnt(0)
	v_pk_fma_f32 v[24:25], v[62:63], v[20:21], 0 op_sel_hi:[1,1,0]
	v_pk_fma_f32 v[8:9], v[56:57], v[8:9], 0 op_sel_hi:[1,1,0]
	v_pk_fma_f32 v[10:11], v[58:59], v[10:11], 0 op_sel_hi:[1,1,0]
	v_pk_fma_f32 v[12:13], v[60:61], v[12:13], 0 op_sel_hi:[1,1,0]
	v_mov_b32_e32 v20, v24
	v_mov_b32_e32 v21, v25
	s_or_b64 exec, exec, s[78:79]
	s_and_saveexec_b64 s[78:79], s[58:59]
	s_cbranch_execz .LBB0_209
.LBB0_303:
	v_lshl_add_u64 v[20:21], s[12:13], 0, v[196:197]
	v_mad_u64_u32 v[52:53], vcc, v20, s91, v[0:1]
	v_mad_i32_i24 v53, v21, s91, v53
	ds_read_b128 v[56:59], v28 offset:2560
	ds_read_b128 v[60:63], v28 offset:2576
	ds_read_b128 v[64:67], v28 offset:2592
	ds_read_b128 v[68:71], v28 offset:2608
	v_lshlrev_b32_e32 v20, 16, v148
	v_and_b32_e32 v21, 0xffff0000, v148
	s_waitcnt lgkmcnt(3)
	v_pk_fma_f32 v[22:23], v[56:57], v[20:21], v[22:23]
	v_lshlrev_b32_e32 v20, 16, v149
	v_and_b32_e32 v21, 0xffff0000, v149
	v_pk_fma_f32 v[18:19], v[58:59], v[20:21], v[18:19]
	v_lshlrev_b32_e32 v20, 16, v150
	v_and_b32_e32 v21, 0xffff0000, v150
	s_waitcnt lgkmcnt(2)
	v_pk_fma_f32 v[16:17], v[60:61], v[20:21], v[16:17]
	v_lshlrev_b32_e32 v20, 16, v151
	v_and_b32_e32 v21, 0xffff0000, v151
	v_pk_fma_f32 v[14:15], v[62:63], v[20:21], v[14:15]
	v_lshlrev_b32_e32 v20, 16, v152
	v_and_b32_e32 v21, 0xffff0000, v152
	s_waitcnt lgkmcnt(1)
	v_pk_fma_f32 v[8:9], v[64:65], v[20:21], v[8:9]
	v_lshlrev_b32_e32 v20, 16, v153
	v_and_b32_e32 v21, 0xffff0000, v153
	v_pk_fma_f32 v[10:11], v[66:67], v[20:21], v[10:11]
	v_lshlrev_b32_e32 v20, 16, v154
	v_and_b32_e32 v21, 0xffff0000, v154
	s_waitcnt lgkmcnt(0)
	v_pk_fma_f32 v[12:13], v[68:69], v[20:21], v[12:13]
	v_lshlrev_b32_e32 v20, 16, v155
	v_and_b32_e32 v21, 0xffff0000, v155
	v_pk_fma_f32 v[20:21], v[70:71], v[20:21], v[24:25]
	s_or_b64 exec, exec, s[78:79]
	s_and_saveexec_b64 s[78:79], s[54:55]
	s_cbranch_execz .LBB0_210
.LBB0_304:
	v_mov_b32_e32 v5, v197
	v_lshl_add_u64 v[24:25], s[12:13], 0, v[4:5]
	v_mad_u64_u32 v[52:53], vcc, v24, s91, v[0:1]
	v_mad_i32_i24 v53, v25, s91, v53
	ds_read_b128 v[56:59], v28 offset:3072
	ds_read_b128 v[60:63], v28 offset:3088
	ds_read_b128 v[64:67], v28 offset:3104
	ds_read_b128 v[68:71], v28 offset:3120
	v_lshlrev_b32_e32 v24, 16, v176
	v_and_b32_e32 v25, 0xffff0000, v176
	s_waitcnt lgkmcnt(3)
	v_pk_fma_f32 v[22:23], v[56:57], v[24:25], v[22:23]
	v_lshlrev_b32_e32 v24, 16, v177
	v_and_b32_e32 v25, 0xffff0000, v177
	v_pk_fma_f32 v[18:19], v[58:59], v[24:25], v[18:19]
	v_lshlrev_b32_e32 v24, 16, v178
	v_and_b32_e32 v25, 0xffff0000, v178
	s_waitcnt lgkmcnt(2)
	v_pk_fma_f32 v[16:17], v[60:61], v[24:25], v[16:17]
	v_lshlrev_b32_e32 v24, 16, v179
	v_and_b32_e32 v25, 0xffff0000, v179
	v_pk_fma_f32 v[14:15], v[62:63], v[24:25], v[14:15]
	v_lshlrev_b32_e32 v24, 16, v180
	v_and_b32_e32 v25, 0xffff0000, v180
	s_waitcnt lgkmcnt(1)
	v_pk_fma_f32 v[8:9], v[64:65], v[24:25], v[8:9]
	v_lshlrev_b32_e32 v24, 16, v181
	v_and_b32_e32 v25, 0xffff0000, v181
	v_pk_fma_f32 v[10:11], v[66:67], v[24:25], v[10:11]
	v_lshlrev_b32_e32 v24, 16, v182
	v_and_b32_e32 v25, 0xffff0000, v182
	s_waitcnt lgkmcnt(0)
	v_pk_fma_f32 v[12:13], v[68:69], v[24:25], v[12:13]
	v_lshlrev_b32_e32 v24, 16, v183
	v_and_b32_e32 v25, 0xffff0000, v183
	v_pk_fma_f32 v[20:21], v[70:71], v[24:25], v[20:21]
	s_or_b64 exec, exec, s[78:79]
	s_and_saveexec_b64 s[78:79], s[52:53]
	s_cbranch_execnz .LBB0_211
	s_branch .LBB0_212
.LBB0_305:
	v_mov_b32_e32 v7, v197
	v_lshl_add_u64 v[6:7], s[12:13], 0, v[6:7]
	v_mad_u64_u32 v[8:9], s[56:57], v6, s91, v[0:1]
	v_mad_i32_i24 v9, v7, s91, v9
	ds_read_b128 v[10:13], v28 offset:4096
	ds_read_b128 v[42:45], v28 offset:4112
	ds_read_b128 v[46:49], v28 offset:4128
	ds_read_b128 v[50:53], v28 offset:4144
	v_lshlrev_b32_e32 v14, 16, v132
	v_and_b32_e32 v15, 0xffff0000, v132
	v_lshlrev_b32_e32 v6, 16, v133
	v_and_b32_e32 v7, 0xffff0000, v133
	s_waitcnt lgkmcnt(3)
	v_pk_fma_f32 v[18:19], v[12:13], v[6:7], 0 op_sel_hi:[1,1,0]
	v_lshlrev_b32_e32 v6, 16, v134
	v_and_b32_e32 v7, 0xffff0000, v134
	s_waitcnt lgkmcnt(2)
	v_pk_fma_f32 v[16:17], v[42:43], v[6:7], 0 op_sel_hi:[1,1,0]
	v_lshlrev_b32_e32 v6, 16, v135
	v_and_b32_e32 v7, 0xffff0000, v135
	v_pk_fma_f32 v[20:21], v[10:11], v[14:15], 0 op_sel_hi:[1,1,0]
	v_pk_fma_f32 v[14:15], v[44:45], v[6:7], 0 op_sel_hi:[1,1,0]
	v_lshlrev_b32_e32 v6, 16, v136
	v_and_b32_e32 v7, 0xffff0000, v136
	s_waitcnt lgkmcnt(1)
	v_pk_fma_f32 v[12:13], v[46:47], v[6:7], 0 op_sel_hi:[1,1,0]
	v_lshlrev_b32_e32 v6, 16, v137
	v_and_b32_e32 v7, 0xffff0000, v137
	v_pk_fma_f32 v[10:11], v[48:49], v[6:7], 0 op_sel_hi:[1,1,0]
	v_lshlrev_b32_e32 v6, 16, v138
	v_and_b32_e32 v7, 0xffff0000, v138
	s_waitcnt lgkmcnt(0)
	v_pk_fma_f32 v[8:9], v[50:51], v[6:7], 0 op_sel_hi:[1,1,0]
	v_lshlrev_b32_e32 v6, 16, v139
	v_and_b32_e32 v7, 0xffff0000, v139
	v_pk_fma_f32 v[24:25], v[52:53], v[6:7], 0 op_sel_hi:[1,1,0]
	s_nop 0
	v_mov_b32_e32 v22, v24
	v_mov_b32_e32 v23, v25
	s_or_b64 exec, exec, s[78:79]
	s_and_saveexec_b64 s[56:57], s[58:59]
	s_cbranch_execz .LBB0_214
.LBB0_306:
	v_lshl_add_u64 v[6:7], s[12:13], 0, v[196:197]
	v_mad_u64_u32 v[22:23], s[58:59], v6, s91, v[0:1]
	v_mad_i32_i24 v23, v7, s91, v23
	ds_read_b128 v[50:53], v28 offset:4608
	ds_read_b128 v[54:57], v28 offset:4624
	ds_read_b128 v[58:61], v28 offset:4640
	ds_read_b128 v[62:65], v28 offset:4656
	v_lshlrev_b32_e32 v6, 16, v156
	v_and_b32_e32 v7, 0xffff0000, v156
	s_waitcnt lgkmcnt(3)
	v_pk_fma_f32 v[20:21], v[50:51], v[6:7], v[20:21]
	v_lshlrev_b32_e32 v6, 16, v157
	v_and_b32_e32 v7, 0xffff0000, v157
	v_pk_fma_f32 v[18:19], v[52:53], v[6:7], v[18:19]
	v_lshlrev_b32_e32 v6, 16, v158
	v_and_b32_e32 v7, 0xffff0000, v158
	s_waitcnt lgkmcnt(2)
	v_pk_fma_f32 v[16:17], v[54:55], v[6:7], v[16:17]
	v_lshlrev_b32_e32 v6, 16, v159
	v_and_b32_e32 v7, 0xffff0000, v159
	v_pk_fma_f32 v[14:15], v[56:57], v[6:7], v[14:15]
	v_lshlrev_b32_e32 v6, 16, v164
	v_and_b32_e32 v7, 0xffff0000, v164
	s_waitcnt lgkmcnt(1)
	v_pk_fma_f32 v[12:13], v[58:59], v[6:7], v[12:13]
	v_lshlrev_b32_e32 v6, 16, v165
	v_and_b32_e32 v7, 0xffff0000, v165
	v_pk_fma_f32 v[10:11], v[60:61], v[6:7], v[10:11]
	v_lshlrev_b32_e32 v6, 16, v166
	v_and_b32_e32 v7, 0xffff0000, v166
	s_waitcnt lgkmcnt(0)
	v_pk_fma_f32 v[8:9], v[62:63], v[6:7], v[8:9]
	v_lshlrev_b32_e32 v6, 16, v167
	v_and_b32_e32 v7, 0xffff0000, v167
	v_pk_fma_f32 v[22:23], v[64:65], v[6:7], v[24:25]
	s_or_b64 exec, exec, s[56:57]
	s_and_saveexec_b64 s[56:57], s[54:55]
	s_cbranch_execz .LBB0_215
.LBB0_307:
	v_mov_b32_e32 v5, v197
	v_lshl_add_u64 v[4:5], s[12:13], 0, v[4:5]
	v_mad_u64_u32 v[24:25], s[54:55], v4, s91, v[0:1]
	v_mad_i32_i24 v25, v5, s91, v25
	ds_read_b128 v[46:49], v28 offset:5120
	ds_read_b128 v[50:53], v28 offset:5136
	ds_read_b128 v[54:57], v28 offset:5152
	ds_read_b128 v[58:61], v28 offset:5168
	v_lshlrev_b32_e32 v24, 16, v184
	v_and_b32_e32 v25, 0xffff0000, v184
	s_waitcnt lgkmcnt(3)
	v_pk_fma_f32 v[20:21], v[46:47], v[24:25], v[20:21]
	v_lshlrev_b32_e32 v24, 16, v185
	v_and_b32_e32 v25, 0xffff0000, v185
	v_pk_fma_f32 v[18:19], v[48:49], v[24:25], v[18:19]
	v_lshlrev_b32_e32 v24, 16, v186
	v_and_b32_e32 v25, 0xffff0000, v186
	s_waitcnt lgkmcnt(2)
	v_pk_fma_f32 v[16:17], v[50:51], v[24:25], v[16:17]
	v_lshlrev_b32_e32 v24, 16, v187
	v_and_b32_e32 v25, 0xffff0000, v187
	v_pk_fma_f32 v[14:15], v[52:53], v[24:25], v[14:15]
	v_lshlrev_b32_e32 v24, 16, v188
	v_and_b32_e32 v25, 0xffff0000, v188
	v_lshlrev_b32_e32 v4, 16, v189
	v_and_b32_e32 v5, 0xffff0000, v189
	s_waitcnt lgkmcnt(1)
	v_pk_fma_f32 v[10:11], v[56:57], v[4:5], v[10:11]
	v_lshlrev_b32_e32 v4, 16, v190
	v_and_b32_e32 v5, 0xffff0000, v190
	s_waitcnt lgkmcnt(0)
	v_pk_fma_f32 v[8:9], v[58:59], v[4:5], v[8:9]
	v_lshlrev_b32_e32 v4, 16, v191
	v_and_b32_e32 v5, 0xffff0000, v191
	v_pk_fma_f32 v[12:13], v[54:55], v[24:25], v[12:13]
	v_pk_fma_f32 v[22:23], v[60:61], v[4:5], v[22:23]
	s_or_b64 exec, exec, s[56:57]
	s_and_saveexec_b64 s[54:55], s[52:53]
	s_cbranch_execnz .LBB0_216
	s_branch .LBB0_217

.LBB0_377:
	s_or_b64 exec, exec, s[76:77]
	s_waitcnt lgkmcnt(0)
	s_barrier
	s_ashr_i32 s79, s78, 31
	s_mov_b64 s[76:77], -1
	s_and_b64 vcc, exec, s[6:7]
	s_cbranch_vccz .LBB0_381
	s_waitcnt vmcnt(16)
	v_mov_b32_e32 v242, 0x3020706
	v_mov_b32_e32 v243, 0x5040100
	v_cndmask_b32_e64 v242, v242, v243, s[40:41]
	v_or_b32_e32 v0, s78, v210
	v_ashrrev_i32_e32 v1, 31, v0
	s_lshl_b64 s[28:29], s[78:79], 14
	v_lshl_add_u64 v[0:1], v[0:1], 2, s[8:9]
	v_lshl_add_u64 v[24:25], v[214:215], 0, s[28:29]
	global_load_dword v164, v[0:1], off
	global_load_dwordx4 v[4:7], v[24:25], off
	global_load_dwordx4 v[12:15], v[24:25], off offset:1024
	global_load_dwordx4 v[20:23], v[24:25], off offset:2048
	global_load_dwordx4 v[28:31], v[24:25], off offset:3072
	s_ashr_i32 s76, s26, 2
	s_lshl_b32 s4, s24, 1
	s_ashr_i32 s77, s76, 31
	s_and_b32 s4, s4, 0x300
	s_lshl_b64 s[76:77], s[76:77], 21
	s_or_b32 s4, s76, s4
	s_add_u32 s27, s17, s4
	v_mov_b32_e32 v32, 0
	s_addc_u32 s28, s20, s77
	s_mov_b32 s29, 0
	s_mov_b64 s[78:79], 0
	v_mov_b32_e32 v33, v32
	v_mov_b32_e32 v34, v32
	v_mov_b32_e32 v35, v32
	v_mov_b32_e32 v36, v32
	v_mov_b32_e32 v37, v32
	v_mov_b32_e32 v38, v32
	v_mov_b32_e32 v39, v32
	v_mov_b32_e32 v40, v32
	v_mov_b32_e32 v41, v32
	v_mov_b32_e32 v42, v32
	v_mov_b32_e32 v43, v32
	v_mov_b32_e32 v44, v32
	v_mov_b32_e32 v45, v32
	v_mov_b32_e32 v46, v32
	v_mov_b32_e32 v47, v32
	v_mov_b32_e32 v48, v32
	v_mov_b32_e32 v49, v32
	v_mov_b32_e32 v50, v32
	v_mov_b32_e32 v51, v32
	s_waitcnt vmcnt(5)
	v_mov_b32_e32 v52, v32
	v_mov_b32_e32 v53, v32
	v_mov_b32_e32 v54, v32
	v_mov_b32_e32 v55, v32
	v_mov_b32_e32 v56, v32
	v_mov_b32_e32 v57, v32
	v_mov_b32_e32 v58, v32
	v_mov_b32_e32 v59, v32
	v_mov_b32_e32 v60, v32
	v_mov_b32_e32 v61, v32
	v_mov_b32_e32 v62, v32
	v_mov_b32_e32 v63, v32
	v_mov_b32_e32 v64, v32
	v_mov_b32_e32 v65, v32
	v_mov_b32_e32 v66, v32
	v_mov_b32_e32 v67, v32
	v_mov_b32_e32 v68, v32
	v_mov_b32_e32 v69, v32
	v_mov_b32_e32 v70, v32
	v_mov_b32_e32 v71, v32
	v_mov_b32_e32 v72, v32
	v_mov_b32_e32 v73, v32
	v_mov_b32_e32 v74, v32
	v_mov_b32_e32 v75, v32
	v_mov_b32_e32 v76, v32
	v_mov_b32_e32 v77, v32
	v_mov_b32_e32 v78, v32
	v_mov_b32_e32 v79, v32
	v_mov_b32_e32 v80, v32
	v_mov_b32_e32 v81, v32
	v_mov_b32_e32 v82, v32
	v_mov_b32_e32 v83, v32
	v_mov_b32_e32 v84, v32
	v_mov_b32_e32 v85, v32
	v_mov_b32_e32 v86, v32
	v_mov_b32_e32 v87, v32
	v_mov_b32_e32 v88, v32
	v_mov_b32_e32 v89, v32
	v_mov_b32_e32 v90, v32
	v_mov_b32_e32 v91, v32
	v_mov_b32_e32 v92, v32
	v_mov_b32_e32 v93, v32
	v_mov_b32_e32 v94, v32
	v_mov_b32_e32 v95, v32
	s_waitcnt vmcnt(3)
	v_lshlrev_b32_e32 v0, 16, v4
	v_and_b32_e32 v1, 0xffff0000, v4
	v_lshlrev_b32_e32 v2, 16, v5
	v_and_b32_e32 v3, 0xffff0000, v5
	v_lshlrev_b32_e32 v4, 16, v6
	v_and_b32_e32 v5, 0xffff0000, v6
	v_lshlrev_b32_e32 v6, 16, v7
	v_and_b32_e32 v7, 0xffff0000, v7
	s_waitcnt vmcnt(2)
	v_lshlrev_b32_e32 v8, 16, v12
	v_and_b32_e32 v9, 0xffff0000, v12
	v_lshlrev_b32_e32 v10, 16, v13
	v_and_b32_e32 v11, 0xffff0000, v13
	v_lshlrev_b32_e32 v12, 16, v14
	v_and_b32_e32 v13, 0xffff0000, v14
	v_lshlrev_b32_e32 v14, 16, v15
	v_and_b32_e32 v15, 0xffff0000, v15
	s_waitcnt vmcnt(1)
	v_lshlrev_b32_e32 v16, 16, v20
	v_and_b32_e32 v17, 0xffff0000, v20
	v_lshlrev_b32_e32 v18, 16, v21
	v_and_b32_e32 v19, 0xffff0000, v21
	v_lshlrev_b32_e32 v20, 16, v22
	v_and_b32_e32 v21, 0xffff0000, v22
	v_lshlrev_b32_e32 v22, 16, v23
	v_and_b32_e32 v23, 0xffff0000, v23
	s_waitcnt vmcnt(0)
	v_lshlrev_b32_e32 v24, 16, v28
	v_and_b32_e32 v25, 0xffff0000, v28
	v_lshlrev_b32_e32 v26, 16, v29
	v_and_b32_e32 v27, 0xffff0000, v29
	v_lshlrev_b32_e32 v28, 16, v30
	v_and_b32_e32 v29, 0xffff0000, v30
	v_lshlrev_b32_e32 v30, 16, v31
	v_and_b32_e32 v31, 0xffff0000, v31
.LBB0_379:
	s_bitcmp1_b32 s29, 0
	s_cselect_b32 s34, 0xf400, 0
	s_add_i32 s30, s22, s29
	s_ashr_i32 s31, s30, 31
	s_lshl_b64 s[30:31], s[30:31], 14
	v_lshl_add_u64 v[240:241], v[214:215], 0, s[30:31]
	v_add_u32_e32 v194, s34, v235
	v_readlane_b32 s4, v164, s29
	s_add_i32 s29, s29, 1
	v_add_u32_e32 v165, v194, v236
	v_add_u32_e32 v194, v194, v244
	v_add_u32_e32 v195, v194, v236
	ds_read_b128 v[96:99], v165
	ds_read_b128 v[166:169], v165 offset:32
	ds_read_b128 v[100:103], v165 offset:8704
	ds_read_b128 v[170:173], v165 offset:8736
	ds_read_b128 v[104:107], v165 offset:17408
	ds_read_b128 v[174:177], v165 offset:17440
	ds_read_b128 v[108:111], v165 offset:26112
	ds_read_b128 v[178:181], v165 offset:26144
	v_cvt_pk_bf16_f32 v182, v80, v81
	v_cvt_pk_bf16_f32 v183, v82, v83
	v_cvt_pk_bf16_f32 v184, v84, v85
	v_cvt_pk_bf16_f32 v185, v86, v87
	s_waitcnt lgkmcnt(7)
	s_nop 0
	v_mfma_f32_32x32x16_bf16 v[128:143], v[96:99], v[182:185], v[0:15]
	s_waitcnt lgkmcnt(5)
	v_mfma_f32_32x32x16_bf16 v[144:159], v[100:103], v[182:185], v[16:31]
	s_waitcnt lgkmcnt(3)
	v_mfma_f32_32x32x16_bf16 v[112:127], v[104:107], v[182:185], 0
	s_waitcnt lgkmcnt(1)
	v_mfma_f32_32x32x16_bf16 v[96:111], v[108:111], v[182:185], 0
	global_load_dwordx4 v[0:3], v[240:241], off
	global_load_dwordx4 v[4:7], v[240:241], off offset:1024
	global_load_dwordx4 v[8:11], v[240:241], off offset:2048
	global_load_dwordx4 v[12:15], v[240:241], off offset:3072
	ds_read_b128 v[182:185], v165 offset:26176
	ds_read_b128 v[186:189], v165 offset:17472
	ds_read_b128 v[190:193], v165 offset:8768
	ds_read_b128 v[220:223], v165 offset:64
	v_cvt_pk_bf16_f32 v246, v88, v89
	v_cvt_pk_bf16_f32 v247, v90, v91
	v_cvt_pk_bf16_f32 v248, v92, v93
	v_cvt_pk_bf16_f32 v249, v94, v95
	s_nop 1
	v_mfma_f32_32x32x16_bf16 v[128:143], v[166:169], v[246:249], v[128:143]
	v_mfma_f32_32x32x16_bf16 v[144:159], v[170:173], v[246:249], v[144:159]
	v_mfma_f32_32x32x16_bf16 v[112:127], v[174:177], v[246:249], v[112:127]
	s_waitcnt lgkmcnt(4)
	v_mfma_f32_32x32x16_bf16 v[96:111], v[178:181], v[246:249], v[96:111]
	ds_read_b128 v[166:169], v165 offset:96
	ds_read_b128 v[170:173], v165 offset:8800
	ds_read_b128 v[174:177], v165 offset:17504
	ds_read_b128 v[178:181], v165 offset:26208
	v_cvt_pk_bf16_f32 v246, v64, v65
	v_cvt_pk_bf16_f32 v247, v66, v67
	v_cvt_pk_bf16_f32 v248, v68, v69
	v_cvt_pk_bf16_f32 v249, v70, v71
	s_waitcnt lgkmcnt(4)
	s_nop 0
	v_mfma_f32_32x32x16_bf16 v[128:143], v[220:223], v[246:249], v[128:143]
	v_mfma_f32_32x32x16_bf16 v[144:159], v[190:193], v[246:249], v[144:159]
	v_mfma_f32_32x32x16_bf16 v[112:127], v[186:189], v[246:249], v[112:127]
	v_mfma_f32_32x32x16_bf16 v[96:111], v[182:185], v[246:249], v[96:111]
	ds_read_b128 v[182:185], v165 offset:26240
	ds_read_b128 v[186:189], v165 offset:17536
	ds_read_b128 v[190:193], v165 offset:8832
	ds_read_b128 v[220:223], v165 offset:128
	v_cvt_pk_bf16_f32 v246, v72, v73
	v_cvt_pk_bf16_f32 v247, v74, v75
	v_cvt_pk_bf16_f32 v248, v76, v77
	v_cvt_pk_bf16_f32 v249, v78, v79
	s_waitcnt lgkmcnt(7)
	s_nop 0
	v_mfma_f32_32x32x16_bf16 v[128:143], v[166:169], v[246:249], v[128:143]
	s_waitcnt lgkmcnt(6)
	v_mfma_f32_32x32x16_bf16 v[144:159], v[170:173], v[246:249], v[144:159]
	s_waitcnt lgkmcnt(5)
	v_mfma_f32_32x32x16_bf16 v[112:127], v[174:177], v[246:249], v[112:127]
	s_waitcnt lgkmcnt(4)
	v_mfma_f32_32x32x16_bf16 v[96:111], v[178:181], v[246:249], v[96:111]
	ds_read_b128 v[166:169], v165 offset:160
	ds_read_b128 v[170:173], v165 offset:8864
	ds_read_b128 v[174:177], v165 offset:17568
	ds_read_b128 v[178:181], v165 offset:26272
	v_cvt_pk_bf16_f32 v246, v48, v49
	v_cvt_pk_bf16_f32 v247, v50, v51
	v_cvt_pk_bf16_f32 v248, v52, v53
	v_cvt_pk_bf16_f32 v249, v54, v55
	s_waitcnt lgkmcnt(4)
	s_nop 0
	v_mfma_f32_32x32x16_bf16 v[128:143], v[220:223], v[246:249], v[128:143]
	v_mfma_f32_32x32x16_bf16 v[144:159], v[190:193], v[246:249], v[144:159]
	v_mfma_f32_32x32x16_bf16 v[112:127], v[186:189], v[246:249], v[112:127]
	v_mfma_f32_32x32x16_bf16 v[96:111], v[182:185], v[246:249], v[96:111]
	ds_read_b128 v[182:185], v165 offset:26304
	ds_read_b128 v[186:189], v165 offset:17600
	ds_read_b128 v[190:193], v165 offset:8896
	ds_read_b128 v[220:223], v165 offset:192
	v_cvt_pk_bf16_f32 v246, v56, v57
	v_cvt_pk_bf16_f32 v247, v58, v59
	v_cvt_pk_bf16_f32 v248, v60, v61
	v_cvt_pk_bf16_f32 v249, v62, v63
	s_waitcnt lgkmcnt(7)
	s_nop 0
	v_mfma_f32_32x32x16_bf16 v[128:143], v[166:169], v[246:249], v[128:143]
	s_waitcnt lgkmcnt(6)
	v_mfma_f32_32x32x16_bf16 v[144:159], v[170:173], v[246:249], v[144:159]
	s_waitcnt lgkmcnt(5)
	v_mfma_f32_32x32x16_bf16 v[112:127], v[174:177], v[246:249], v[112:127]
	s_waitcnt lgkmcnt(4)
	v_mfma_f32_32x32x16_bf16 v[96:111], v[178:181], v[246:249], v[96:111]
	ds_read_b128 v[166:169], v165 offset:224
	ds_read_b128 v[170:173], v165 offset:8928
	ds_read_b128 v[174:177], v165 offset:17632
	ds_read_b128 v[178:181], v165 offset:26336
	v_cvt_pk_bf16_f32 v246, v32, v33
	v_cvt_pk_bf16_f32 v247, v34, v35
	v_cvt_pk_bf16_f32 v248, v36, v37
	v_cvt_pk_bf16_f32 v249, v38, v39
	s_waitcnt lgkmcnt(4)
	s_nop 0
	v_mfma_f32_32x32x16_bf16 v[128:143], v[220:223], v[246:249], v[128:143]
	v_mfma_f32_32x32x16_bf16 v[144:159], v[190:193], v[246:249], v[144:159]
	v_mfma_f32_32x32x16_bf16 v[112:127], v[186:189], v[246:249], v[112:127]
	v_mfma_f32_32x32x16_bf16 v[96:111], v[182:185], v[246:249], v[96:111]
	ds_read_b128 v[182:185], v195 offset:57952
	ds_read_b128 v[186:189], v195 offset:57920
	ds_read_b128 v[190:193], v195 offset:57888
	ds_read_b128 v[220:223], v195 offset:57856
	ds_read_b128 v[246:249], v195 offset:53248
	ds_read_b128 v[250:253], v195 offset:53280
	v_cvt_pk_bf16_f32 v204, v40, v41
	v_cvt_pk_bf16_f32 v205, v42, v43
	v_cvt_pk_bf16_f32 v206, v44, v45
	v_cvt_pk_bf16_f32 v207, v46, v47
	s_waitcnt lgkmcnt(9)
	s_nop 0
	v_mfma_f32_32x32x16_bf16 v[128:143], v[166:169], v[204:207], v[128:143]
	s_waitcnt lgkmcnt(8)
	v_mfma_f32_32x32x16_bf16 v[144:159], v[170:173], v[204:207], v[144:159]
	s_waitcnt lgkmcnt(7)
	v_mfma_f32_32x32x16_bf16 v[112:127], v[174:177], v[204:207], v[112:127]
	s_waitcnt lgkmcnt(6)
	v_mfma_f32_32x32x16_bf16 v[96:111], v[178:181], v[204:207], v[96:111]
	v_add_u32_e32 v165, v194, v196
	s_nop 4
	v_cvt_pk_bf16_f32 v128, v128, v129
	v_cvt_pk_bf16_f32 v129, v130, v131
	v_cvt_pk_bf16_f32 v130, v132, v133
	v_cvt_pk_bf16_f32 v131, v134, v135
	v_cvt_pk_bf16_f32 v132, v136, v137
	v_cvt_pk_bf16_f32 v133, v138, v139
	v_cvt_pk_bf16_f32 v134, v140, v141
	v_cvt_pk_bf16_f32 v135, v142, v143
	v_cvt_pk_bf16_f32 v136, v144, v145
	v_cvt_pk_bf16_f32 v137, v146, v147
	v_cvt_pk_bf16_f32 v138, v148, v149
	v_cvt_pk_bf16_f32 v139, v150, v151
	v_cvt_pk_bf16_f32 v140, v152, v153
	v_cvt_pk_bf16_f32 v141, v154, v155
	v_cvt_pk_bf16_f32 v142, v156, v157
	v_cvt_pk_bf16_f32 v143, v158, v159
	ds_read_b128 v[144:147], v165 offset:34816
	ds_read_b128 v[148:151], v165 offset:34848
	ds_read_b128 v[152:155], v165 offset:34880
	ds_read_b128 v[156:159], v165 offset:34912
	s_waitcnt lgkmcnt(6)
	v_mfma_f32_32x32x16_bf16 v[96:111], v[220:223], v[128:131], v[96:111]
	v_mfma_f32_32x32x16_bf16 v[96:111], v[190:193], v[132:135], v[96:111]
	s_waitcnt lgkmcnt(5)
	v_mfma_f32_32x32x16_bf16 v[112:127], v[246:249], v[128:131], v[112:127]
	v_mfma_f32_32x32x16_bf16 v[96:111], v[186:189], v[136:139], v[96:111]
	s_waitcnt lgkmcnt(4)
	v_mfma_f32_32x32x16_bf16 v[112:127], v[250:253], v[132:135], v[112:127]
	v_mfma_f32_32x32x16_bf16 v[96:111], v[182:185], v[140:143], v[96:111]
	ds_read_b128 v[166:169], v165 offset:39424
	ds_read_b128 v[170:173], v165 offset:39456
	ds_read_b128 v[174:177], v165 offset:39520
	ds_read_b128 v[178:181], v165 offset:39488
	v_mul_f32_e64 v94, v94, s4
	v_mul_f32_e64 v95, v95, s4
	v_pk_mul_f32 v[92:93], v[92:93], s[4:5] op_sel_hi:[1,0]
	v_pk_mul_f32 v[90:91], v[90:91], s[4:5] op_sel_hi:[1,0]
	v_pk_mul_f32 v[88:89], v[88:89], s[4:5] op_sel_hi:[1,0]
	v_pk_mul_f32 v[86:87], v[86:87], s[4:5] op_sel_hi:[1,0]
	v_pk_mul_f32 v[84:85], v[84:85], s[4:5] op_sel_hi:[1,0]
	v_pk_mul_f32 v[82:83], v[82:83], s[4:5] op_sel_hi:[1,0]
	v_pk_mul_f32 v[80:81], v[80:81], s[4:5] op_sel_hi:[1,0]
	s_waitcnt lgkmcnt(7)
	s_nop 0
	v_mfma_f32_32x32x16_bf16 v[80:95], v[144:147], v[128:131], v[80:95]
	s_add_u32 s80, s27, s78
	s_addc_u32 s81, s28, s79
	v_cvt_pk_bf16_f32 v182, v112, v113
	v_cvt_pk_bf16_f32 v183, v114, v115
	v_cvt_pk_bf16_f32 v184, v116, v117
	v_cvt_pk_bf16_f32 v185, v118, v119
	s_waitcnt lgkmcnt(6)
	v_mfma_f32_32x32x16_bf16 v[80:95], v[148:151], v[132:135], v[80:95]
	v_cvt_pk_bf16_f32 v186, v120, v121
	v_cvt_pk_bf16_f32 v187, v122, v123
	v_cvt_pk_bf16_f32 v188, v124, v125
	v_cvt_pk_bf16_f32 v189, v126, v127
	s_waitcnt lgkmcnt(5)
	v_mfma_f32_32x32x16_bf16 v[80:95], v[152:155], v[136:139], v[80:95]
	v_mov_b32_dpp v190, v182 quad_perm:[1,0,3,2] row_mask:0xf bank_mask:0xf
	v_mov_b32_dpp v191, v183 quad_perm:[1,0,3,2] row_mask:0xf bank_mask:0xf
	v_mov_b32_dpp v192, v184 quad_perm:[1,0,3,2] row_mask:0xf bank_mask:0xf
	v_mov_b32_dpp v193, v185 quad_perm:[1,0,3,2] row_mask:0xf bank_mask:0xf
	v_add_u32_e32 v246, 0x2000, v213
	s_waitcnt lgkmcnt(4)
	v_mfma_f32_32x32x16_bf16 v[80:95], v[156:159], v[140:143], v[80:95]
	v_mov_b32_dpp v220, v186 quad_perm:[1,0,3,2] row_mask:0xf bank_mask:0xf
	v_mov_b32_dpp v221, v187 quad_perm:[1,0,3,2] row_mask:0xf bank_mask:0xf
	v_mov_b32_dpp v222, v188 quad_perm:[1,0,3,2] row_mask:0xf bank_mask:0xf
	v_mov_b32_dpp v223, v189 quad_perm:[1,0,3,2] row_mask:0xf bank_mask:0xf
	v_add_u32_e32 v247, 0x4000, v213
	ds_read_b128 v[144:147], v165 offset:44096
	ds_read_b128 v[148:151], v165 offset:44128
	ds_read_b128 v[152:155], v165 offset:44032
	ds_read_b128 v[156:159], v165 offset:44064
	v_mul_f32_e64 v78, v78, s4
	v_mul_f32_e64 v79, v79, s4
	v_pk_mul_f32 v[76:77], v[76:77], s[4:5] op_sel_hi:[1,0]
	v_pk_mul_f32 v[74:75], v[74:75], s[4:5] op_sel_hi:[1,0]
	v_pk_mul_f32 v[72:73], v[72:73], s[4:5] op_sel_hi:[1,0]
	v_pk_mul_f32 v[70:71], v[70:71], s[4:5] op_sel_hi:[1,0]
	v_pk_mul_f32 v[68:69], v[68:69], s[4:5] op_sel_hi:[1,0]
	v_pk_mul_f32 v[66:67], v[66:67], s[4:5] op_sel_hi:[1,0]
	v_pk_mul_f32 v[64:65], v[64:65], s[4:5] op_sel_hi:[1,0]
	s_waitcnt lgkmcnt(6)
	s_nop 0
	v_mfma_f32_32x32x16_bf16 v[64:79], v[170:173], v[128:131], v[64:79]
	v_perm_b32 v182, v190, v182, v242
	v_perm_b32 v183, v191, v183, v242
	v_perm_b32 v184, v192, v184, v242
	v_perm_b32 v185, v193, v185, v242
	v_add_u32_e32 v248, 0x6000, v213
	v_mfma_f32_32x32x16_bf16 v[64:79], v[166:169], v[132:135], v[64:79]
	v_perm_b32 v186, v220, v186, v242
	v_perm_b32 v187, v221, v187, v242
	v_perm_b32 v188, v222, v188, v242
	v_perm_b32 v189, v223, v189, v242
	s_waitcnt lgkmcnt(5)
	v_mfma_f32_32x32x16_bf16 v[64:79], v[174:177], v[136:139], v[64:79]
	global_store_dword v213, v182, s[80:81]
	global_store_dword v213, v183, s[80:81] offset:2048
	global_store_dword v246, v184, s[80:81]
	global_store_dword v246, v185, s[80:81] offset:2048
	s_waitcnt lgkmcnt(4)
	v_mfma_f32_32x32x16_bf16 v[64:79], v[178:181], v[140:143], v[64:79]
	global_store_dword v247, v186, s[80:81]
	global_store_dword v247, v187, s[80:81] offset:2048
	global_store_dword v248, v188, s[80:81]
	global_store_dword v248, v189, s[80:81] offset:2048
	ds_read_b128 v[166:169], v165 offset:48736
	ds_read_b128 v[170:173], v165 offset:48704
	ds_read_b128 v[174:177], v165 offset:48640
	ds_read_b128 v[178:181], v165 offset:48672
	v_mul_f32_e64 v62, v62, s4
	v_mul_f32_e64 v63, v63, s4
	v_pk_mul_f32 v[60:61], v[60:61], s[4:5] op_sel_hi:[1,0]
	v_pk_mul_f32 v[58:59], v[58:59], s[4:5] op_sel_hi:[1,0]
	v_pk_mul_f32 v[56:57], v[56:57], s[4:5] op_sel_hi:[1,0]
	v_pk_mul_f32 v[54:55], v[54:55], s[4:5] op_sel_hi:[1,0]
	v_pk_mul_f32 v[52:53], v[52:53], s[4:5] op_sel_hi:[1,0]
	v_pk_mul_f32 v[50:51], v[50:51], s[4:5] op_sel_hi:[1,0]
	v_pk_mul_f32 v[48:49], v[48:49], s[4:5] op_sel_hi:[1,0]
	s_waitcnt lgkmcnt(7)
	s_nop 0
	v_mfma_f32_32x32x16_bf16 v[48:63], v[144:147], v[128:131], v[48:63]
	v_cvt_pk_bf16_f32 v182, v96, v97
	v_cvt_pk_bf16_f32 v183, v98, v99
	v_cvt_pk_bf16_f32 v184, v100, v101
	v_cvt_pk_bf16_f32 v185, v102, v103
	s_waitcnt lgkmcnt(6)
	v_mfma_f32_32x32x16_bf16 v[48:63], v[148:151], v[132:135], v[48:63]
	v_cvt_pk_bf16_f32 v186, v104, v105
	v_cvt_pk_bf16_f32 v187, v106, v107
	v_cvt_pk_bf16_f32 v188, v108, v109
	v_cvt_pk_bf16_f32 v189, v110, v111
	s_waitcnt lgkmcnt(5)
	v_mfma_f32_32x32x16_bf16 v[48:63], v[152:155], v[136:139], v[48:63]
	v_mov_b32_dpp v190, v182 quad_perm:[1,0,3,2] row_mask:0xf bank_mask:0xf
	v_mov_b32_dpp v191, v183 quad_perm:[1,0,3,2] row_mask:0xf bank_mask:0xf
	v_mov_b32_dpp v192, v184 quad_perm:[1,0,3,2] row_mask:0xf bank_mask:0xf
	v_mov_b32_dpp v193, v185 quad_perm:[1,0,3,2] row_mask:0xf bank_mask:0xf
	v_add_u32_e32 v246, 0x8000, v213
	s_waitcnt lgkmcnt(4)
	v_mfma_f32_32x32x16_bf16 v[48:63], v[156:159], v[140:143], v[48:63]
	v_mov_b32_dpp v220, v186 quad_perm:[1,0,3,2] row_mask:0xf bank_mask:0xf
	v_mov_b32_dpp v221, v187 quad_perm:[1,0,3,2] row_mask:0xf bank_mask:0xf
	v_mov_b32_dpp v222, v188 quad_perm:[1,0,3,2] row_mask:0xf bank_mask:0xf
	v_mov_b32_dpp v223, v189 quad_perm:[1,0,3,2] row_mask:0xf bank_mask:0xf
	v_add_u32_e32 v247, 0xa000, v213
	v_pk_mul_f32 v[46:47], v[46:47], s[4:5] op_sel_hi:[1,0]
	v_pk_mul_f32 v[44:45], v[44:45], s[4:5] op_sel_hi:[1,0]
	v_pk_mul_f32 v[42:43], v[42:43], s[4:5] op_sel_hi:[1,0]
	v_pk_mul_f32 v[40:41], v[40:41], s[4:5] op_sel_hi:[1,0]
	v_pk_mul_f32 v[38:39], v[38:39], s[4:5] op_sel_hi:[1,0]
	v_pk_mul_f32 v[36:37], v[36:37], s[4:5] op_sel_hi:[1,0]
	v_pk_mul_f32 v[34:35], v[34:35], s[4:5] op_sel_hi:[1,0]
	v_pk_mul_f32 v[32:33], v[32:33], s[4:5] op_sel_hi:[1,0]
	s_waitcnt lgkmcnt(3)
	s_nop 0
	v_mfma_f32_32x32x16_bf16 v[32:47], v[166:169], v[128:131], v[32:47]
	v_perm_b32 v182, v190, v182, v242
	v_perm_b32 v183, v191, v183, v242
	v_perm_b32 v184, v192, v184, v242
	v_perm_b32 v185, v193, v185, v242
	v_add_u32_e32 v248, 0xc000, v213
	s_waitcnt lgkmcnt(2)
	v_mfma_f32_32x32x16_bf16 v[32:47], v[170:173], v[132:135], v[32:47]
	v_perm_b32 v186, v220, v186, v242
	v_perm_b32 v187, v221, v187, v242
	v_perm_b32 v188, v222, v188, v242
	v_perm_b32 v189, v223, v189, v242
	v_add_u32_e32 v249, 0xe000, v213
	s_waitcnt lgkmcnt(0)
	v_mfma_f32_32x32x16_bf16 v[32:47], v[178:181], v[136:139], v[32:47]
	global_store_dword v246, v182, s[80:81]
	global_store_dword v246, v183, s[80:81] offset:2048
	global_store_dword v247, v184, s[80:81]
	global_store_dword v247, v185, s[80:81] offset:2048
	v_mfma_f32_32x32x16_bf16 v[32:47], v[174:177], v[140:143], v[32:47]
	global_store_dword v248, v186, s[80:81]
	global_store_dword v248, v187, s[80:81] offset:2048
	global_store_dword v249, v188, s[80:81]
	global_store_dword v249, v189, s[80:81] offset:2048
	s_waitcnt vmcnt(16)
	v_and_b32_e32 v31, 0xffff0000, v15
	v_lshlrev_b32_e32 v30, 16, v15
	v_and_b32_e32 v29, 0xffff0000, v14
	v_lshlrev_b32_e32 v28, 16, v14
	v_and_b32_e32 v27, 0xffff0000, v13
	v_lshlrev_b32_e32 v26, 16, v13
	v_and_b32_e32 v25, 0xffff0000, v12
	v_lshlrev_b32_e32 v24, 16, v12
	v_and_b32_e32 v23, 0xffff0000, v11
	v_lshlrev_b32_e32 v22, 16, v11
	v_and_b32_e32 v21, 0xffff0000, v10
	v_lshlrev_b32_e32 v20, 16, v10
	v_and_b32_e32 v19, 0xffff0000, v9
	v_lshlrev_b32_e32 v18, 16, v9
	v_and_b32_e32 v17, 0xffff0000, v8
	v_lshlrev_b32_e32 v16, 16, v8
	v_and_b32_e32 v15, 0xffff0000, v7
	v_lshlrev_b32_e32 v14, 16, v7
	v_and_b32_e32 v13, 0xffff0000, v6
	v_lshlrev_b32_e32 v12, 16, v6
	v_and_b32_e32 v11, 0xffff0000, v5
	v_lshlrev_b32_e32 v10, 16, v5
	v_and_b32_e32 v9, 0xffff0000, v4
	v_lshlrev_b32_e32 v8, 16, v4
	v_and_b32_e32 v7, 0xffff0000, v3
	v_lshlrev_b32_e32 v6, 16, v3
	v_and_b32_e32 v5, 0xffff0000, v2
	v_lshlrev_b32_e32 v4, 16, v2
	v_and_b32_e32 v3, 0xffff0000, v1
	v_lshlrev_b32_e32 v2, 16, v1
	v_and_b32_e32 v1, 0xffff0000, v0
	v_lshlrev_b32_e32 v0, 16, v0
	s_waitcnt lgkmcnt(0)
	s_barrier
	s_add_u32 s78, s78, 0x10000
	s_addc_u32 s79, s79, 0
	s_cmp_eq_u32 s78, 0x1f0000
	s_cbranch_scc0 .LBB0_379
	s_add_u32 s4, s17, s76
	s_addc_u32 s27, s20, s77
	s_lshl_b32 s28, s26, 8
	s_and_b32 s28, s28, 0x300
	s_add_u32 s4, s4, s28
	s_addc_u32 s27, s27, 0
	ds_read_b128 v[96:99], v237 offset:62464
	ds_read_b128 v[128:131], v237 offset:62496
	ds_read_b128 v[100:103], v238 offset:8704
	ds_read_b128 v[132:135], v238 offset:8736
	ds_read_b128 v[104:107], v238 offset:17408
	ds_read_b128 v[136:139], v238 offset:17440
	ds_read_b128 v[108:111], v238 offset:26112
	ds_read_b128 v[140:143], v238 offset:26144
	v_cvt_pk_bf16_f32 v80, v80, v81
	v_cvt_pk_bf16_f32 v81, v82, v83
	v_cvt_pk_bf16_f32 v82, v84, v85
	v_cvt_pk_bf16_f32 v83, v86, v87
	s_waitcnt lgkmcnt(7)
	s_nop 0
	v_mfma_f32_32x32x16_bf16 v[0:15], v[96:99], v[80:83], v[0:15]
	s_waitcnt lgkmcnt(5)
	v_mfma_f32_32x32x16_bf16 v[16:31], v[100:103], v[80:83], v[16:31]
	s_waitcnt lgkmcnt(3)
	v_mfma_f32_32x32x16_bf16 v[112:127], v[104:107], v[80:83], 0
	s_waitcnt lgkmcnt(1)
	v_mfma_f32_32x32x16_bf16 v[96:111], v[108:111], v[80:83], 0
	ds_read_b128 v[80:83], v238 offset:26176
	ds_read_b128 v[84:87], v238 offset:17472
	ds_read_b128 v[144:147], v238 offset:8768
	ds_read_b128 v[148:151], v237 offset:62528
	v_cvt_pk_bf16_f32 v88, v88, v89
	v_cvt_pk_bf16_f32 v89, v90, v91
	v_cvt_pk_bf16_f32 v90, v92, v93
	v_cvt_pk_bf16_f32 v91, v94, v95
	s_nop 1
	v_mfma_f32_32x32x16_bf16 v[0:15], v[128:131], v[88:91], v[0:15]
	v_mfma_f32_32x32x16_bf16 v[16:31], v[132:135], v[88:91], v[16:31]
	v_mfma_f32_32x32x16_bf16 v[112:127], v[136:139], v[88:91], v[112:127]
	s_waitcnt lgkmcnt(4)
	v_mfma_f32_32x32x16_bf16 v[96:111], v[140:143], v[88:91], v[96:111]
	ds_read_b128 v[88:91], v237 offset:62560
	ds_read_b128 v[92:95], v238 offset:8800
	ds_read_b128 v[128:131], v238 offset:17504
	ds_read_b128 v[132:135], v238 offset:26208
	v_cvt_pk_bf16_f32 v64, v64, v65
	v_cvt_pk_bf16_f32 v65, v66, v67
	v_cvt_pk_bf16_f32 v66, v68, v69
	v_cvt_pk_bf16_f32 v67, v70, v71
	s_waitcnt lgkmcnt(4)
	s_nop 0
	v_mfma_f32_32x32x16_bf16 v[0:15], v[148:151], v[64:67], v[0:15]
	v_mfma_f32_32x32x16_bf16 v[16:31], v[144:147], v[64:67], v[16:31]
	v_mfma_f32_32x32x16_bf16 v[112:127], v[84:87], v[64:67], v[112:127]
	v_mfma_f32_32x32x16_bf16 v[96:111], v[80:83], v[64:67], v[96:111]
	ds_read_b128 v[64:67], v238 offset:26240
	ds_read_b128 v[68:71], v238 offset:17536
	ds_read_b128 v[80:83], v238 offset:8832
	ds_read_b128 v[84:87], v237 offset:62592
	v_cvt_pk_bf16_f32 v72, v72, v73
	v_cvt_pk_bf16_f32 v73, v74, v75
	v_cvt_pk_bf16_f32 v74, v76, v77
	v_cvt_pk_bf16_f32 v75, v78, v79
	s_waitcnt lgkmcnt(7)
	s_nop 0
	v_mfma_f32_32x32x16_bf16 v[0:15], v[88:91], v[72:75], v[0:15]
	s_waitcnt lgkmcnt(6)
	v_mfma_f32_32x32x16_bf16 v[16:31], v[92:95], v[72:75], v[16:31]
	s_waitcnt lgkmcnt(5)
	v_mfma_f32_32x32x16_bf16 v[112:127], v[128:131], v[72:75], v[112:127]
	s_waitcnt lgkmcnt(4)
	v_mfma_f32_32x32x16_bf16 v[96:111], v[132:135], v[72:75], v[96:111]
	ds_read_b128 v[72:75], v237 offset:62624
	ds_read_b128 v[76:79], v238 offset:8864
	ds_read_b128 v[88:91], v238 offset:17568
	ds_read_b128 v[92:95], v238 offset:26272
	v_cvt_pk_bf16_f32 v48, v48, v49
	v_cvt_pk_bf16_f32 v49, v50, v51
	v_cvt_pk_bf16_f32 v50, v52, v53
	v_cvt_pk_bf16_f32 v51, v54, v55
	s_waitcnt lgkmcnt(4)
	s_nop 0
	v_mfma_f32_32x32x16_bf16 v[0:15], v[84:87], v[48:51], v[0:15]
	v_mfma_f32_32x32x16_bf16 v[16:31], v[80:83], v[48:51], v[16:31]
	v_mfma_f32_32x32x16_bf16 v[112:127], v[68:71], v[48:51], v[112:127]
	v_mfma_f32_32x32x16_bf16 v[96:111], v[64:67], v[48:51], v[96:111]
	ds_read_b128 v[48:51], v238 offset:26304
	ds_read_b128 v[52:55], v238 offset:17600
	ds_read_b128 v[64:67], v238 offset:8896
	ds_read_b128 v[68:71], v237 offset:62656
	v_cvt_pk_bf16_f32 v56, v56, v57
	v_cvt_pk_bf16_f32 v57, v58, v59
	v_cvt_pk_bf16_f32 v58, v60, v61
	v_cvt_pk_bf16_f32 v59, v62, v63
	s_waitcnt lgkmcnt(7)
	s_nop 0
	v_mfma_f32_32x32x16_bf16 v[0:15], v[72:75], v[56:59], v[0:15]
	s_waitcnt lgkmcnt(6)
	v_mfma_f32_32x32x16_bf16 v[16:31], v[76:79], v[56:59], v[16:31]
	s_waitcnt lgkmcnt(5)
	v_mfma_f32_32x32x16_bf16 v[112:127], v[88:91], v[56:59], v[112:127]
	s_waitcnt lgkmcnt(4)
	v_mfma_f32_32x32x16_bf16 v[96:111], v[92:95], v[56:59], v[96:111]
	ds_read_b128 v[56:59], v237 offset:62688
	ds_read_b128 v[60:63], v238 offset:8928
	ds_read_b128 v[72:75], v238 offset:17632
	ds_read_b128 v[76:79], v238 offset:26336
	v_cvt_pk_bf16_f32 v32, v32, v33
	v_cvt_pk_bf16_f32 v33, v34, v35
	v_cvt_pk_bf16_f32 v34, v36, v37
	v_cvt_pk_bf16_f32 v35, v38, v39
	s_waitcnt lgkmcnt(4)
	s_nop 0
	v_mfma_f32_32x32x16_bf16 v[0:15], v[68:71], v[32:35], v[0:15]
	v_mfma_f32_32x32x16_bf16 v[16:31], v[64:67], v[32:35], v[16:31]
	v_mfma_f32_32x32x16_bf16 v[112:127], v[52:55], v[32:35], v[112:127]
	v_mfma_f32_32x32x16_bf16 v[96:111], v[48:51], v[32:35], v[96:111]
	ds_read_b128 v[32:35], v239 offset:4704
	ds_read_b128 v[36:39], v239 offset:4672
	ds_read_b128 v[48:51], v239 offset:4640
	ds_read_b128 v[52:55], v239 offset:4608
	ds_read_b128 v[64:67], v239
	ds_read_b128 v[68:71], v239 offset:32
	v_cvt_pk_bf16_f32 v40, v40, v41
	v_cvt_pk_bf16_f32 v41, v42, v43
	v_cvt_pk_bf16_f32 v42, v44, v45
	v_cvt_pk_bf16_f32 v43, v46, v47
	s_waitcnt lgkmcnt(9)
	s_nop 0
	v_mfma_f32_32x32x16_bf16 v[0:15], v[56:59], v[40:43], v[0:15]
	s_waitcnt lgkmcnt(8)
	v_mfma_f32_32x32x16_bf16 v[16:31], v[60:63], v[40:43], v[16:31]
	s_waitcnt lgkmcnt(7)
	v_mfma_f32_32x32x16_bf16 v[112:127], v[72:75], v[40:43], v[112:127]
	s_waitcnt lgkmcnt(6)
	v_mfma_f32_32x32x16_bf16 v[96:111], v[76:79], v[40:43], v[96:111]
	s_nop 5
	v_cvt_pk_bf16_f32 v0, v0, v1
	v_cvt_pk_bf16_f32 v1, v2, v3
	v_cvt_pk_bf16_f32 v2, v4, v5
	v_cvt_pk_bf16_f32 v3, v6, v7
	v_cvt_pk_bf16_f32 v4, v8, v9
	v_cvt_pk_bf16_f32 v5, v10, v11
	v_cvt_pk_bf16_f32 v6, v12, v13
	v_cvt_pk_bf16_f32 v7, v14, v15
	v_cvt_pk_bf16_f32 v8, v16, v17
	v_cvt_pk_bf16_f32 v9, v18, v19
	v_cvt_pk_bf16_f32 v10, v20, v21
	v_cvt_pk_bf16_f32 v11, v22, v23
	v_cvt_pk_bf16_f32 v12, v24, v25
	v_cvt_pk_bf16_f32 v13, v26, v27
	v_cvt_pk_bf16_f32 v14, v28, v29
	v_cvt_pk_bf16_f32 v15, v30, v31
	s_waitcnt lgkmcnt(2)
	v_mfma_f32_32x32x16_bf16 v[96:111], v[52:55], v[0:3], v[96:111]
	v_mfma_f32_32x32x16_bf16 v[96:111], v[48:51], v[4:7], v[96:111]
	s_waitcnt lgkmcnt(1)
	v_mfma_f32_32x32x16_bf16 v[112:127], v[64:67], v[0:3], v[112:127]
	v_mfma_f32_32x32x16_bf16 v[96:111], v[36:39], v[8:11], v[96:111]
	s_waitcnt lgkmcnt(0)
	v_mfma_f32_32x32x16_bf16 v[112:127], v[68:71], v[4:7], v[112:127]
	v_mfma_f32_32x32x16_bf16 v[96:111], v[32:35], v[12:15], v[96:111]
	v_mov_b32_e32 v1, v197
	v_mov_b32_e32 v2, v197
	s_add_u32 s76, s4, 0x1f0000
	s_nop 7
	v_mov_b32_dpp v1, v112 quad_perm:[1,0,3,2] row_mask:0xf bank_mask:0xf
	v_mov_b32_e32 v0, v213
	v_mov_b32_dpp v2, v113 quad_perm:[1,0,3,2] row_mask:0xf bank_mask:0xf
	v_cndmask_b32_e64 v1, v113, v1, s[40:41]
	s_addc_u32 s77, s27, 0
	v_cndmask_b32_e64 v2, v2, v112, s[40:41]
	v_cvt_pk_bf16_f32 v1, v2, v1
	global_store_dword v0, v1, s[76:77]
	v_mov_b32_e32 v1, v197
	v_mov_b32_e32 v2, v197
	s_nop 0
	v_mov_b32_dpp v1, v114 quad_perm:[1,0,3,2] row_mask:0xf bank_mask:0xf
	v_mov_b32_dpp v2, v115 quad_perm:[1,0,3,2] row_mask:0xf bank_mask:0xf
	v_cndmask_b32_e64 v2, v2, v114, s[40:41]
	v_cndmask_b32_e64 v1, v115, v1, s[40:41]
	v_cvt_pk_bf16_f32 v1, v2, v1
	v_add_u32_e32 v2, 0x800, v0
	global_store_dword v2, v1, s[76:77]
	v_mov_b32_e32 v1, v197
	v_mov_b32_e32 v2, v197
	s_nop 0
	v_mov_b32_dpp v1, v116 quad_perm:[1,0,3,2] row_mask:0xf bank_mask:0xf
	v_mov_b32_dpp v2, v117 quad_perm:[1,0,3,2] row_mask:0xf bank_mask:0xf
	v_cndmask_b32_e64 v2, v2, v116, s[40:41]
	v_cndmask_b32_e64 v1, v117, v1, s[40:41]
	v_cvt_pk_bf16_f32 v1, v2, v1
	v_add_u32_e32 v2, 0x2000, v0
	global_store_dword v2, v1, s[76:77]
	v_mov_b32_e32 v1, v197
	v_mov_b32_e32 v2, v197
	s_nop 0
	v_mov_b32_dpp v1, v118 quad_perm:[1,0,3,2] row_mask:0xf bank_mask:0xf
	v_mov_b32_dpp v2, v119 quad_perm:[1,0,3,2] row_mask:0xf bank_mask:0xf
	v_cndmask_b32_e64 v2, v2, v118, s[40:41]
	v_cndmask_b32_e64 v1, v119, v1, s[40:41]
	v_cvt_pk_bf16_f32 v1, v2, v1
	v_add_u32_e32 v2, 0x2800, v0
	global_store_dword v2, v1, s[76:77]
	v_mov_b32_e32 v1, v197
	v_mov_b32_e32 v2, v197
	s_nop 0
	v_mov_b32_dpp v1, v120 quad_perm:[1,0,3,2] row_mask:0xf bank_mask:0xf
	v_mov_b32_dpp v2, v121 quad_perm:[1,0,3,2] row_mask:0xf bank_mask:0xf
	v_cndmask_b32_e64 v2, v2, v120, s[40:41]
	v_cndmask_b32_e64 v1, v121, v1, s[40:41]
	v_cvt_pk_bf16_f32 v1, v2, v1
	v_add_u32_e32 v2, 0x4000, v0
	global_store_dword v2, v1, s[76:77]
	v_mov_b32_e32 v1, v197
	v_mov_b32_e32 v2, v197
	s_nop 0
	v_mov_b32_dpp v1, v122 quad_perm:[1,0,3,2] row_mask:0xf bank_mask:0xf
	v_mov_b32_dpp v2, v123 quad_perm:[1,0,3,2] row_mask:0xf bank_mask:0xf
	v_cndmask_b32_e64 v2, v2, v122, s[40:41]
	v_cndmask_b32_e64 v1, v123, v1, s[40:41]
	v_cvt_pk_bf16_f32 v1, v2, v1
	v_add_u32_e32 v2, 0x4800, v0
	global_store_dword v2, v1, s[76:77]
	v_mov_b32_e32 v1, v197
	v_mov_b32_e32 v2, v197
	s_nop 0
	v_mov_b32_dpp v1, v124 quad_perm:[1,0,3,2] row_mask:0xf bank_mask:0xf
	v_mov_b32_dpp v2, v125 quad_perm:[1,0,3,2] row_mask:0xf bank_mask:0xf
	v_cndmask_b32_e64 v2, v2, v124, s[40:41]
	v_cndmask_b32_e64 v1, v125, v1, s[40:41]
	v_cvt_pk_bf16_f32 v1, v2, v1
	v_add_u32_e32 v2, 0x6000, v0
	global_store_dword v2, v1, s[76:77]
	v_mov_b32_e32 v1, v197
	v_mov_b32_e32 v2, v197
	s_nop 0
	v_mov_b32_dpp v1, v126 quad_perm:[1,0,3,2] row_mask:0xf bank_mask:0xf
	v_mov_b32_dpp v2, v127 quad_perm:[1,0,3,2] row_mask:0xf bank_mask:0xf
	v_cndmask_b32_e64 v2, v2, v126, s[40:41]
	v_cndmask_b32_e64 v1, v127, v1, s[40:41]
	v_cvt_pk_bf16_f32 v1, v2, v1
	v_add_u32_e32 v2, 0x6800, v0
	global_store_dword v2, v1, s[76:77]
	v_mov_b32_e32 v1, v197
	v_mov_b32_e32 v2, v197
	s_nop 0
	v_mov_b32_dpp v1, v96 quad_perm:[1,0,3,2] row_mask:0xf bank_mask:0xf
	v_mov_b32_dpp v2, v97 quad_perm:[1,0,3,2] row_mask:0xf bank_mask:0xf
	v_cndmask_b32_e64 v2, v2, v96, s[40:41]
	v_cndmask_b32_e64 v1, v97, v1, s[40:41]
	v_cvt_pk_bf16_f32 v1, v2, v1
	v_add_u32_e32 v2, 0x8000, v0
	global_store_dword v2, v1, s[76:77]
	v_mov_b32_e32 v1, v197
	v_mov_b32_e32 v2, v197
	s_nop 0
	v_mov_b32_dpp v1, v98 quad_perm:[1,0,3,2] row_mask:0xf bank_mask:0xf
	v_mov_b32_dpp v2, v99 quad_perm:[1,0,3,2] row_mask:0xf bank_mask:0xf
	v_cndmask_b32_e64 v2, v2, v98, s[40:41]
	v_cndmask_b32_e64 v1, v99, v1, s[40:41]
	v_cvt_pk_bf16_f32 v1, v2, v1
	v_add_u32_e32 v2, 0x8800, v0
	global_store_dword v2, v1, s[76:77]
	v_mov_b32_e32 v1, v197
	v_mov_b32_e32 v2, v197
	s_nop 0
	v_mov_b32_dpp v1, v100 quad_perm:[1,0,3,2] row_mask:0xf bank_mask:0xf
	v_mov_b32_dpp v2, v101 quad_perm:[1,0,3,2] row_mask:0xf bank_mask:0xf
	v_cndmask_b32_e64 v2, v2, v100, s[40:41]
	v_cndmask_b32_e64 v1, v101, v1, s[40:41]
	v_cvt_pk_bf16_f32 v1, v2, v1
	v_add_u32_e32 v2, 0xa000, v0
	global_store_dword v2, v1, s[76:77]
	v_mov_b32_e32 v1, v197
	v_mov_b32_e32 v2, v197
	s_nop 0
	v_mov_b32_dpp v1, v102 quad_perm:[1,0,3,2] row_mask:0xf bank_mask:0xf
	v_mov_b32_dpp v2, v103 quad_perm:[1,0,3,2] row_mask:0xf bank_mask:0xf
	v_cndmask_b32_e64 v2, v2, v102, s[40:41]
	v_cndmask_b32_e64 v1, v103, v1, s[40:41]
	v_cvt_pk_bf16_f32 v1, v2, v1
	v_add_u32_e32 v2, 0xa800, v0
	global_store_dword v2, v1, s[76:77]
	v_mov_b32_e32 v1, v197
	v_mov_b32_e32 v2, v197
	s_nop 0
	v_mov_b32_dpp v1, v104 quad_perm:[1,0,3,2] row_mask:0xf bank_mask:0xf
	v_mov_b32_dpp v2, v105 quad_perm:[1,0,3,2] row_mask:0xf bank_mask:0xf
	v_cndmask_b32_e64 v2, v2, v104, s[40:41]
	v_cndmask_b32_e64 v1, v105, v1, s[40:41]
	v_cvt_pk_bf16_f32 v1, v2, v1
	v_add_u32_e32 v2, 0xc000, v0
	global_store_dword v2, v1, s[76:77]
	v_mov_b32_e32 v1, v197
	v_mov_b32_e32 v2, v197
	s_nop 0
	v_mov_b32_dpp v1, v106 quad_perm:[1,0,3,2] row_mask:0xf bank_mask:0xf
	v_mov_b32_dpp v2, v107 quad_perm:[1,0,3,2] row_mask:0xf bank_mask:0xf
	v_cndmask_b32_e64 v2, v2, v106, s[40:41]
	v_cndmask_b32_e64 v1, v107, v1, s[40:41]
	v_cvt_pk_bf16_f32 v1, v2, v1
	v_add_u32_e32 v2, 0xc800, v0
	global_store_dword v2, v1, s[76:77]
	v_mov_b32_e32 v1, v197
	v_mov_b32_e32 v2, v197
	s_nop 0
	v_mov_b32_dpp v1, v108 quad_perm:[1,0,3,2] row_mask:0xf bank_mask:0xf
	v_mov_b32_dpp v2, v109 quad_perm:[1,0,3,2] row_mask:0xf bank_mask:0xf
	v_cndmask_b32_e64 v2, v2, v108, s[40:41]
	v_cndmask_b32_e64 v1, v109, v1, s[40:41]
	v_cvt_pk_bf16_f32 v1, v2, v1
	v_add_u32_e32 v2, 0xe000, v0
	global_store_dword v2, v1, s[76:77]
	v_mov_b32_e32 v1, v197
	v_mov_b32_e32 v2, v197
	v_add_u32_e32 v0, 0xe800, v0
	v_mov_b32_dpp v1, v110 quad_perm:[1,0,3,2] row_mask:0xf bank_mask:0xf
	v_mov_b32_dpp v2, v111 quad_perm:[1,0,3,2] row_mask:0xf bank_mask:0xf
	v_cndmask_b32_e64 v1, v111, v1, s[40:41]
	v_cndmask_b32_e64 v2, v2, v110, s[40:41]
	v_cvt_pk_bf16_f32 v1, v2, v1
	global_store_dword v0, v1, s[76:77]
	s_waitcnt lgkmcnt(0)
	s_barrier
	s_mov_b64 s[76:77], 0
	s_mov_b64 s[34:35], 0x800
